# P6 K loop carries 37% of the window-cache copy (1 block load+store per iteration); P7 second-round units split 4-way along K over 16 workgroups; P7 epilogue copy share 60% -> 23%
# speedup vs baseline: 1.0202x; 1.0178x over previous
.LBB0_717:
	s_or_b64 exec, exec, s[0:1]
	s_min_u32 s100, s88, 238
	s_lshl_b32 s100, s100, 3
	s_mul_i32 s32, s88, 40
	s_add_i32 s32, s32, s100
	v_writelane_b32 v247, s32, 62
	s_nop 0
	s_cmp_lt_u32 s88, 238
	s_cselect_b32 s32, 47, 39
	v_writelane_b32 v247, s32, 61
	s_nop 0
	s_mov_b32 s32, 0
	v_writelane_b32 v247, s32, 60
	s_nop 0
	v_readlane_b32 s32, v247, 60
	v_readlane_b32 s100, v247, 61
	s_min_u32 s32, s32, s100
	v_readlane_b32 s100, v247, 62
	s_add_i32 s32, s32, s100
	s_min_u32 s32, s32, 0x2f6f
	s_lshr_b32 s100, s32, 1
	s_add_i32 s100, s100, 0x2808
	s_mul_i32 s101, s100, 0x8081
	s_lshr_b32 s101, s101, 24
	s_mul_i32 s98, s101, 0x1fe
	s_sub_i32 s100, s100, s98
	s_lshl_b32 s101, s101, 22
	s_lshl_b32 s100, s100, 13
	s_add_u32 s100, s100, s101
	s_bitcmp1_b32 s32, 0
	s_cselect_b32 s98, s84, s82
	s_cselect_b32 s99, s85, s83
	s_add_u32 s98, s98, s100
	s_addc_u32 s99, s99, 0
	s_add_u32 s98, s98, 0x4000
	s_addc_u32 s99, s99, 0
	v_lshlrev_b32_e32 v236, 4, v222
	global_load_dwordx4 v[252:255], v236, s[98:99] nt
	s_mov_b32 s32, 1
	v_writelane_b32 v247, s32, 60
	s_nop 0
	s_cmpk_lt_i32 s88, 0x5ee
	s_cselect_b64 s[0:1], -1, 0
	v_mov_b32_e32 v8, v222
	s_waitcnt lgkmcnt(0)
	s_barrier
	s_and_b64 vcc, exec, s[0:1]
	v_readfirstlane_b32 s8, v8
	s_cbranch_vccz .LBB0_719
	v_readlane_b32 s2, v247, 18
	s_mul_i32 s6, s2, 0xbe
	s_mulk_i32 s2, 0xbd
	s_add_i32 s7, s2, 6
	v_readlane_b32 s2, v247, 19
	v_readlane_b32 s3, v247, 20
	s_and_b64 s[2:3], s[2:3], exec
	s_cselect_b32 s2, s6, s7
	v_readlane_b32 s3, v247, 25
	s_add_i32 s2, s2, s3
	s_mul_hi_i32 s3, s2, 0x2e8ba2e9
	s_lshr_b32 s6, s3, 31
	s_ashr_i32 s3, s3, 5
	s_add_i32 s3, s3, s6
	s_lshl_b32 s6, s3, 3
	s_sub_i32 s7, 0x45, s6
	s_min_u32 s7, s7, 8
	s_mulk_i32 s3, 0xb0
	s_sub_i32 s9, s2, s3
	v_cvt_f32_ubyte0_e32 v1, s7
	v_cvt_f32_i32_e32 v0, s9
	v_rcp_iflag_f32_e32 v2, v1
	s_ashr_i32 s2, s9, 30
	s_or_b32 s10, s2, 1
	v_mul_f32_e32 v2, v0, v2
	v_trunc_f32_e32 v2, v2
	v_fma_f32 v0, -v2, v1, v0
	v_cvt_i32_f32_e32 v2, v2
	v_cmp_ge_f32_e64 s[2:3], |v0|, v1
	s_and_b64 s[2:3], s[2:3], exec
	s_cselect_b32 s2, s10, 0
	v_readfirstlane_b32 s3, v2
	s_add_i32 s3, s3, s2
	s_sext_i32_i16 s2, s3
	s_mul_i32 s3, s3, s7
	s_sub_i32 s3, s9, s3
	s_sext_i32_i16 s3, s3
	s_add_i32 s16, s6, s3

.LBB0_740:
	ds_read_b128 v[44:47], v205
	ds_read_b128 v[48:51], v205 offset:1024
	ds_read_b128 v[52:55], v205 offset:2048
	ds_read_b128 v[56:59], v205 offset:3072
	ds_read_b128 v[60:63], v206
	ds_read_b128 v[64:67], v206 offset:1024
	ds_read_b128 v[68:71], v206 offset:2048
	ds_read_b128 v[160:163], v206 offset:3072
	s_add_u32 s12, s10, s8
	s_addc_u32 s13, s11, s9
	s_add_u32 s12, s12, 0x100
	s_addc_u32 s13, s13, 0
	s_add_u32 s63, s19, s8
	s_addc_u32 vcc_lo, s55, s9
	s_cmpk_eq_i32 s8, 0x700
	s_cselect_b32 s15, s59, s13
	s_cselect_b32 s14, s58, s12
	s_cselect_b32 s4, s57, s1
	s_cselect_b32 s5, s56, s0
	s_cselect_b32 s13, s3, vcc_lo
	s_cselect_b32 s12, s18, s63
	s_cselect_b32 s63, s97, s17
	v_lshl_add_u64 v[224:225], v[42:43], 0, s[8:9]
	s_add_i32 m0, s65, 0xc000
	ds_read_b128 v[164:167], v207
	ds_read_b128 v[168:171], v207 offset:1024
	ds_read_b128 v[172:175], v207 offset:2048
	ds_read_b128 v[194:197], v207 offset:3072
	ds_read_b128 v[198:201], v207 offset:4096
	ds_read_b128 v[210:213], v207 offset:5120
	ds_read_b128 v[214:217], v207 offset:6144
	ds_read_b128 v[218:221], v207 offset:7168
	global_load_lds_dwordx4 v[224:225], off
	v_lshl_add_u64 v[224:225], v[40:41], 0, s[8:9]
	s_add_i32 m0, s65, 0xe000
	s_nop 0
	global_load_lds_dwordx4 v[224:225], off
	v_readlane_b32 s32, v247, 60
	s_add_i32 s32, s32, -1
	v_readlane_b32 s100, v247, 61
	s_min_u32 s32, s32, s100
	v_readlane_b32 s100, v247, 62
	s_add_i32 s32, s32, s100
	s_min_u32 s32, s32, 0x2f6f
	s_lshr_b32 s100, s32, 1
	s_add_i32 s100, s100, 0x2808
	s_mul_i32 s101, s100, 0x8081
	s_lshr_b32 s101, s101, 24
	s_mul_i32 s98, s101, 0x1fe
	s_sub_i32 s100, s100, s98
	s_lshl_b32 s101, s101, 22
	s_lshl_b32 s100, s100, 13
	s_add_u32 s100, s100, s101
	s_bitcmp1_b32 s32, 0
	s_cselect_b32 s98, s66, s70
	s_cselect_b32 s99, s67, s71
	s_add_u32 s98, s98, s100
	s_addc_u32 s99, s99, 0
	v_lshlrev_b32_e32 v236, 4, v222
	global_store_dwordx4 v236, v[252:255], s[98:99] nt
	v_readlane_b32 s32, v247, 60
	v_readlane_b32 s100, v247, 61
	s_min_u32 s32, s32, s100
	v_readlane_b32 s100, v247, 62
	s_add_i32 s32, s32, s100
	s_min_u32 s32, s32, 0x2f6f
	s_lshr_b32 s100, s32, 1
	s_add_i32 s100, s100, 0x2808
	s_mul_i32 s101, s100, 0x8081
	s_lshr_b32 s101, s101, 24
	s_mul_i32 s98, s101, 0x1fe
	s_sub_i32 s100, s100, s98
	s_lshl_b32 s101, s101, 22
	s_lshl_b32 s100, s100, 13
	s_add_u32 s100, s100, s101
	s_bitcmp1_b32 s32, 0
	s_cselect_b32 s98, s84, s82
	s_cselect_b32 s99, s85, s83
	s_add_u32 s98, s98, s100
	s_addc_u32 s99, s99, 0
	s_add_u32 s98, s98, 0x4000
	s_addc_u32 s99, s99, 0
	v_lshlrev_b32_e32 v236, 4, v222
	global_load_dwordx4 v[252:255], v236, s[98:99] nt
	v_readlane_b32 s32, v247, 60
	s_add_i32 s32, s32, 1
	v_writelane_b32 v247, s32, 60
	s_nop 0
	s_waitcnt vmcnt(10)
	s_waitcnt lgkmcnt(0)
	s_barrier
	s_setprio 1
	s_waitcnt lgkmcnt(0)
	v_mfma_f32_16x16x32_bf16 v[156:159], v[44:47], v[164:167], v[156:159]
	v_mfma_f32_16x16x32_bf16 v[152:155], v[52:55], v[164:167], v[152:155]
	v_mfma_f32_16x16x32_bf16 v[140:143], v[44:47], v[172:175], v[140:143]
	v_mfma_f32_16x16x32_bf16 v[136:139], v[52:55], v[172:175], v[136:139]
	v_mfma_f32_16x16x32_bf16 v[124:127], v[44:47], v[198:201], v[124:127]
	v_mfma_f32_16x16x32_bf16 v[120:123], v[52:55], v[198:201], v[120:123]
	v_mfma_f32_16x16x32_bf16 v[108:111], v[44:47], v[214:217], v[108:111]
	v_mfma_f32_16x16x32_bf16 v[104:107], v[52:55], v[214:217], v[104:107]
	v_mfma_f32_16x16x32_bf16 v[156:159], v[48:51], v[168:171], v[156:159]
	v_mfma_f32_16x16x32_bf16 v[152:155], v[56:59], v[168:171], v[152:155]
	v_mfma_f32_16x16x32_bf16 v[140:143], v[48:51], v[194:197], v[140:143]
	v_mfma_f32_16x16x32_bf16 v[136:139], v[56:59], v[194:197], v[136:139]
	v_mfma_f32_16x16x32_bf16 v[124:127], v[48:51], v[210:213], v[124:127]
	v_mfma_f32_16x16x32_bf16 v[120:123], v[56:59], v[210:213], v[120:123]
	v_mfma_f32_16x16x32_bf16 v[108:111], v[48:51], v[218:221], v[108:111]
	v_mfma_f32_16x16x32_bf16 v[104:107], v[56:59], v[218:221], v[104:107]
	s_setprio 0
	s_setprio 1
	v_mfma_f32_16x16x32_bf16 v[148:151], v[60:63], v[164:167], v[148:151]
	v_mfma_f32_16x16x32_bf16 v[144:147], v[68:71], v[164:167], v[144:147]
	v_mfma_f32_16x16x32_bf16 v[132:135], v[60:63], v[172:175], v[132:135]
	v_mfma_f32_16x16x32_bf16 v[128:131], v[68:71], v[172:175], v[128:131]
	v_mfma_f32_16x16x32_bf16 v[116:119], v[60:63], v[198:201], v[116:119]
	v_mfma_f32_16x16x32_bf16 v[112:115], v[68:71], v[198:201], v[112:115]
	v_mfma_f32_16x16x32_bf16 v[100:103], v[60:63], v[214:217], v[100:103]
	v_mfma_f32_16x16x32_bf16 v[96:99], v[68:71], v[214:217], v[96:99]
	v_mfma_f32_16x16x32_bf16 v[148:151], v[64:67], v[168:171], v[148:151]
	v_mfma_f32_16x16x32_bf16 v[144:147], v[160:163], v[168:171], v[144:147]
	v_mfma_f32_16x16x32_bf16 v[132:135], v[64:67], v[194:197], v[132:135]
	v_mfma_f32_16x16x32_bf16 v[128:131], v[160:163], v[194:197], v[128:131]
	v_mfma_f32_16x16x32_bf16 v[116:119], v[64:67], v[210:213], v[116:119]
	v_mfma_f32_16x16x32_bf16 v[112:115], v[160:163], v[210:213], v[112:115]
	v_mfma_f32_16x16x32_bf16 v[100:103], v[64:67], v[218:221], v[100:103]
	v_mfma_f32_16x16x32_bf16 v[96:99], v[160:163], v[218:221], v[96:99]
	s_setprio 0
	s_barrier
	s_add_i32 vcc_lo, s88, s33
	v_lshl_add_u64 v[228:229], s[12:13], 0, v[178:179]
	s_mov_b32 m0, vcc_lo
	ds_read_b128 v[164:167], v207 offset:16384
	ds_read_b128 v[168:171], v207 offset:17408
	ds_read_b128 v[172:175], v207 offset:18432
	ds_read_b128 v[194:197], v207 offset:19456
	ds_read_b128 v[198:201], v207 offset:20480
	ds_read_b128 v[210:213], v207 offset:21504
	ds_read_b128 v[214:217], v207 offset:22528
	ds_read_b128 v[218:221], v207 offset:23552
	global_load_lds_dwordx4 v[228:229], off
	s_add_i32 m0, vcc_lo, 0x2000
	s_add_u32 vcc_lo, s12, 0x40000
	v_lshl_add_u64 v[230:231], s[12:13], 0, v[182:183]
	s_addc_u32 vcc_hi, s13, 0
	s_add_i32 s36, s89, s33
	global_load_lds_dwordx4 v[230:231], off
	v_lshl_add_u64 v[224:225], vcc, 0, v[178:179]
	s_mov_b32 m0, s36
	v_lshl_add_u64 v[232:233], s[14:15], 0, v[176:177]
	global_load_lds_dwordx4 v[224:225], off
	s_add_i32 m0, s36, 0x2000
	v_lshl_add_u64 v[224:225], vcc, 0, v[182:183]
	s_sub_u32 vcc_lo, 0, s63
	global_load_lds_dwordx4 v[224:225], off
	s_mov_b32 m0, s65
	v_lshl_add_u64 v[224:225], s[14:15], 0, v[180:181]
	s_subb_u32 vcc_hi, 0, 0
	global_load_lds_dwordx4 v[232:233], off
	v_lshl_add_u64 v[234:235], v[224:225], 0, vcc
	s_mov_b32 m0, s68
	s_nop 0
	global_load_lds_dwordx4 v[234:235], off
	s_waitcnt vmcnt(10)
	s_waitcnt lgkmcnt(0)
	s_barrier
	s_setprio 1
	s_waitcnt lgkmcnt(0)
	v_mfma_f32_16x16x32_bf16 v[92:95], v[44:47], v[164:167], v[92:95]
	v_mfma_f32_16x16x32_bf16 v[88:91], v[52:55], v[164:167], v[88:91]
	v_mfma_f32_16x16x32_bf16 v[76:79], v[44:47], v[172:175], v[76:79]
	v_mfma_f32_16x16x32_bf16 v[72:75], v[52:55], v[172:175], v[72:75]
	v_mfma_f32_16x16x32_bf16 v[28:31], v[44:47], v[198:201], v[28:31]
	v_mfma_f32_16x16x32_bf16 v[24:27], v[52:55], v[198:201], v[24:27]
	v_mfma_f32_16x16x32_bf16 v[12:15], v[44:47], v[214:217], v[12:15]
	v_mfma_f32_16x16x32_bf16 v[8:11], v[52:55], v[214:217], v[8:11]
	v_mfma_f32_16x16x32_bf16 v[92:95], v[48:51], v[168:171], v[92:95]
	v_mfma_f32_16x16x32_bf16 v[88:91], v[56:59], v[168:171], v[88:91]
	v_mfma_f32_16x16x32_bf16 v[76:79], v[48:51], v[194:197], v[76:79]
	v_mfma_f32_16x16x32_bf16 v[72:75], v[56:59], v[194:197], v[72:75]
	v_mfma_f32_16x16x32_bf16 v[28:31], v[48:51], v[210:213], v[28:31]
	v_mfma_f32_16x16x32_bf16 v[24:27], v[56:59], v[210:213], v[24:27]
	v_mfma_f32_16x16x32_bf16 v[12:15], v[48:51], v[218:221], v[12:15]
	v_mfma_f32_16x16x32_bf16 v[8:11], v[56:59], v[218:221], v[8:11]
	s_setprio 0
	s_setprio 1
	v_mfma_f32_16x16x32_bf16 v[36:39], v[60:63], v[172:175], v[36:39]
	v_mfma_f32_16x16x32_bf16 v[32:35], v[68:71], v[172:175], v[32:35]
	v_mfma_f32_16x16x32_bf16 v[20:23], v[60:63], v[198:201], v[20:23]
	v_mfma_f32_16x16x32_bf16 v[16:19], v[68:71], v[198:201], v[16:19]
	v_mfma_f32_16x16x32_bf16 v[4:7], v[60:63], v[214:217], v[4:7]
	v_mfma_f32_16x16x32_bf16 v[0:3], v[68:71], v[214:217], v[0:3]
	v_mfma_f32_16x16x32_bf16 v[44:47], v[60:63], v[164:167], v[84:87]
	v_mfma_f32_16x16x32_bf16 v[48:51], v[68:71], v[164:167], v[80:83]
	v_mfma_f32_16x16x32_bf16 v[36:39], v[64:67], v[194:197], v[36:39]
	v_mfma_f32_16x16x32_bf16 v[32:35], v[160:163], v[194:197], v[32:35]
	v_mfma_f32_16x16x32_bf16 v[20:23], v[64:67], v[210:213], v[20:23]
	v_mfma_f32_16x16x32_bf16 v[16:19], v[160:163], v[210:213], v[16:19]
	v_mfma_f32_16x16x32_bf16 v[4:7], v[64:67], v[218:221], v[4:7]
	v_mfma_f32_16x16x32_bf16 v[0:3], v[160:163], v[218:221], v[0:3]
	v_mfma_f32_16x16x32_bf16 v[44:47], v[64:67], v[168:171], v[44:47]
	v_mfma_f32_16x16x32_bf16 v[48:51], v[160:163], v[168:171], v[48:51]
	s_setprio 0
	s_barrier
	s_add_i32 s36, 0, 0x18000
	s_add_i32 s37, 0, 0x1c000
	v_add_u32_e32 v64, s36, v204
	v_add_u32_e32 v80, s37, v204
	ds_read_b128 v[52:55], v64
	ds_read_b128 v[56:59], v64 offset:1024
	ds_read_b128 v[60:63], v64 offset:2048
	ds_read_b128 v[64:67], v64 offset:3072
	ds_read_b128 v[68:71], v80
	ds_read_b128 v[160:163], v80 offset:1024
	ds_read_b128 v[164:167], v80 offset:2048
	ds_read_b128 v[168:171], v80 offset:3072
	s_add_u32 s14, s14, s5
	s_addc_u32 s15, s15, s4
	s_mov_b32 m0, s69
	v_lshl_add_u64 v[224:225], s[14:15], 0, v[176:177]
	ds_read_b128 v[80:83], v207 offset:32768
	ds_read_b128 v[84:87], v207 offset:33792
	ds_read_b128 v[172:175], v207 offset:34816
	ds_read_b128 v[194:197], v207 offset:35840
	ds_read_b128 v[198:201], v207 offset:36864
	ds_read_b128 v[210:213], v207 offset:37888
	ds_read_b128 v[214:217], v207 offset:38912
	ds_read_b128 v[218:221], v207 offset:39936
	global_load_lds_dwordx4 v[224:225], off
	v_lshl_add_u64 v[224:225], s[14:15], 0, v[180:181]
	v_lshl_add_u64 v[224:225], v[224:225], 0, vcc
	s_mov_b32 m0, s72
	s_nop 0
	global_load_lds_dwordx4 v[224:225], off
	s_waitcnt vmcnt(10)
	s_waitcnt lgkmcnt(0)
	s_barrier
	s_setprio 1
	s_waitcnt lgkmcnt(0)
	v_mfma_f32_16x16x32_bf16 v[156:159], v[52:55], v[80:83], v[156:159]
	v_mfma_f32_16x16x32_bf16 v[152:155], v[60:63], v[80:83], v[152:155]
	v_mfma_f32_16x16x32_bf16 v[140:143], v[52:55], v[172:175], v[140:143]
	v_mfma_f32_16x16x32_bf16 v[136:139], v[60:63], v[172:175], v[136:139]
	v_mfma_f32_16x16x32_bf16 v[124:127], v[52:55], v[198:201], v[124:127]
	v_mfma_f32_16x16x32_bf16 v[120:123], v[60:63], v[198:201], v[120:123]
	v_mfma_f32_16x16x32_bf16 v[108:111], v[52:55], v[214:217], v[108:111]
	v_mfma_f32_16x16x32_bf16 v[104:107], v[60:63], v[214:217], v[104:107]
	v_mfma_f32_16x16x32_bf16 v[156:159], v[56:59], v[84:87], v[156:159]
	v_mfma_f32_16x16x32_bf16 v[152:155], v[64:67], v[84:87], v[152:155]
	v_mfma_f32_16x16x32_bf16 v[140:143], v[56:59], v[194:197], v[140:143]
	v_mfma_f32_16x16x32_bf16 v[136:139], v[64:67], v[194:197], v[136:139]
	v_mfma_f32_16x16x32_bf16 v[124:127], v[56:59], v[210:213], v[124:127]
	v_mfma_f32_16x16x32_bf16 v[120:123], v[64:67], v[210:213], v[120:123]
	v_mfma_f32_16x16x32_bf16 v[108:111], v[56:59], v[218:221], v[108:111]
	v_mfma_f32_16x16x32_bf16 v[104:107], v[64:67], v[218:221], v[104:107]
	s_setprio 0
	s_setprio 1
	v_mfma_f32_16x16x32_bf16 v[148:151], v[68:71], v[80:83], v[148:151]
	v_mfma_f32_16x16x32_bf16 v[80:83], v[164:167], v[80:83], v[144:147]
	v_mfma_f32_16x16x32_bf16 v[144:147], v[168:171], v[84:87], v[80:83]
	v_mfma_f32_16x16x32_bf16 v[80:83], v[68:71], v[172:175], v[132:135]
	v_mfma_f32_16x16x32_bf16 v[132:135], v[160:163], v[194:197], v[80:83]
	v_mfma_f32_16x16x32_bf16 v[80:83], v[164:167], v[172:175], v[128:131]
	v_mfma_f32_16x16x32_bf16 v[128:131], v[168:171], v[194:197], v[80:83]
	v_mfma_f32_16x16x32_bf16 v[80:83], v[68:71], v[198:201], v[116:119]
	v_mfma_f32_16x16x32_bf16 v[116:119], v[160:163], v[210:213], v[80:83]
	v_mfma_f32_16x16x32_bf16 v[80:83], v[164:167], v[198:201], v[112:115]
	v_mfma_f32_16x16x32_bf16 v[112:115], v[168:171], v[210:213], v[80:83]
	v_mfma_f32_16x16x32_bf16 v[80:83], v[68:71], v[214:217], v[100:103]
	v_mfma_f32_16x16x32_bf16 v[100:103], v[160:163], v[218:221], v[80:83]
	v_mfma_f32_16x16x32_bf16 v[80:83], v[164:167], v[214:217], v[96:99]
	v_mfma_f32_16x16x32_bf16 v[148:151], v[160:163], v[84:87], v[148:151]
	v_mfma_f32_16x16x32_bf16 v[96:99], v[168:171], v[218:221], v[80:83]
	s_setprio 0
	s_barrier
	s_add_i32 s4, s36, s33
	v_lshl_add_u64 v[84:85], v[228:229], 0, s[50:51]
	s_mov_b32 m0, s4
	s_nop 0
	ds_read_b128 v[80:83], v207 offset:49152
	ds_read_b128 v[172:175], v207 offset:50176
	ds_read_b128 v[194:197], v207 offset:51200
	ds_read_b128 v[198:201], v207 offset:52224
	ds_read_b128 v[210:213], v207 offset:53248
	ds_read_b128 v[214:217], v207 offset:54272
	ds_read_b128 v[218:221], v207 offset:55296
	ds_read_b128 v[224:227], v207 offset:56320
	global_load_lds_dwordx4 v[84:85], off
	s_add_i32 m0, s4, 0x2000
	s_add_u32 s12, s12, 0x40080
	v_lshl_add_u64 v[84:85], v[230:231], 0, s[50:51]
	s_addc_u32 s13, s13, 0
	s_add_i32 s4, s37, s33
	global_load_lds_dwordx4 v[84:85], off
	v_lshl_add_u64 v[84:85], s[12:13], 0, v[178:179]
	s_mov_b32 m0, s4
	s_nop 0
	global_load_lds_dwordx4 v[84:85], off
	v_lshl_add_u64 v[84:85], s[12:13], 0, v[182:183]
	s_add_i32 m0, s4, 0x2000
	s_nop 0
	global_load_lds_dwordx4 v[84:85], off
	v_lshl_add_u64 v[84:85], v[232:233], 0, s[50:51]
	s_mov_b32 m0, s75
	s_nop 0
	global_load_lds_dwordx4 v[84:85], off
	v_lshl_add_u64 v[84:85], v[234:235], 0, s[50:51]
	s_mov_b32 m0, s76
	s_nop 0
	global_load_lds_dwordx4 v[84:85], off
	s_waitcnt vmcnt(8)
	s_waitcnt lgkmcnt(0)
	s_barrier
	s_setprio 1
	s_waitcnt lgkmcnt(0)
	v_mfma_f32_16x16x32_bf16 v[84:87], v[52:55], v[80:83], v[92:95]
	v_mfma_f32_16x16x32_bf16 v[92:95], v[56:59], v[172:175], v[84:87]
	v_mfma_f32_16x16x32_bf16 v[84:87], v[60:63], v[80:83], v[88:91]
	v_mfma_f32_16x16x32_bf16 v[76:79], v[52:55], v[194:197], v[76:79]
	v_mfma_f32_16x16x32_bf16 v[72:75], v[60:63], v[194:197], v[72:75]
	v_mfma_f32_16x16x32_bf16 v[28:31], v[52:55], v[210:213], v[28:31]
	v_mfma_f32_16x16x32_bf16 v[24:27], v[60:63], v[210:213], v[24:27]
	v_mfma_f32_16x16x32_bf16 v[12:15], v[52:55], v[218:221], v[12:15]
	v_mfma_f32_16x16x32_bf16 v[8:11], v[60:63], v[218:221], v[8:11]
	v_mfma_f32_16x16x32_bf16 v[88:91], v[64:67], v[172:175], v[84:87]
	v_mfma_f32_16x16x32_bf16 v[76:79], v[56:59], v[198:201], v[76:79]
	v_mfma_f32_16x16x32_bf16 v[72:75], v[64:67], v[198:201], v[72:75]
	v_mfma_f32_16x16x32_bf16 v[28:31], v[56:59], v[214:217], v[28:31]
	v_mfma_f32_16x16x32_bf16 v[24:27], v[64:67], v[214:217], v[24:27]
	v_mfma_f32_16x16x32_bf16 v[12:15], v[56:59], v[224:227], v[12:15]
	v_mfma_f32_16x16x32_bf16 v[8:11], v[64:67], v[224:227], v[8:11]
	s_setprio 0
	s_setprio 1
	v_mfma_f32_16x16x32_bf16 v[44:47], v[68:71], v[80:83], v[44:47]
	v_mfma_f32_16x16x32_bf16 v[84:87], v[160:163], v[172:175], v[44:47]
	v_mfma_f32_16x16x32_bf16 v[44:47], v[164:167], v[80:83], v[48:51]
	v_mfma_f32_16x16x32_bf16 v[36:39], v[68:71], v[194:197], v[36:39]
	v_mfma_f32_16x16x32_bf16 v[32:35], v[164:167], v[194:197], v[32:35]
	v_mfma_f32_16x16x32_bf16 v[20:23], v[68:71], v[210:213], v[20:23]
	v_mfma_f32_16x16x32_bf16 v[16:19], v[164:167], v[210:213], v[16:19]
	v_mfma_f32_16x16x32_bf16 v[4:7], v[68:71], v[218:221], v[4:7]
	v_mfma_f32_16x16x32_bf16 v[0:3], v[164:167], v[218:221], v[0:3]
	v_mfma_f32_16x16x32_bf16 v[80:83], v[168:171], v[172:175], v[44:47]
	v_mfma_f32_16x16x32_bf16 v[36:39], v[160:163], v[198:201], v[36:39]
	v_mfma_f32_16x16x32_bf16 v[32:35], v[168:171], v[198:201], v[32:35]
	v_mfma_f32_16x16x32_bf16 v[20:23], v[160:163], v[214:217], v[20:23]
	v_mfma_f32_16x16x32_bf16 v[16:19], v[168:171], v[214:217], v[16:19]
	v_mfma_f32_16x16x32_bf16 v[4:7], v[160:163], v[224:227], v[4:7]
	v_mfma_f32_16x16x32_bf16 v[0:3], v[168:171], v[224:227], v[0:3]
	s_setprio 0
	s_barrier
	s_add_i32 s62, s62, 2
	s_add_u32 s8, s8, 0x100
	s_addc_u32 s9, s9, 0
	s_cmp_gt_u32 s62, 13
	s_cbranch_scc0 .LBB0_740
	s_and_b64 vcc, exec, s[52:53]
	s_cbranch_vccz .LBB0_743
	s_barrier

.LBB0_970:
	v_readlane_b32 s32, v247, 60
	s_add_i32 s32, s32, -1
	v_readlane_b32 s100, v247, 61
	s_min_u32 s32, s32, s100
	v_readlane_b32 s100, v247, 62
	s_add_i32 s32, s32, s100
	s_min_u32 s32, s32, 0x2f6f
	s_lshr_b32 s100, s32, 1
	s_add_i32 s100, s100, 0x2808
	s_mul_i32 s101, s100, 0x8081
	s_lshr_b32 s101, s101, 24
	s_mul_i32 s98, s101, 0x1fe
	s_sub_i32 s100, s100, s98
	s_lshl_b32 s101, s101, 22
	s_lshl_b32 s100, s100, 13
	s_add_u32 s100, s100, s101
	s_bitcmp1_b32 s32, 0
	s_cselect_b32 s98, s66, s70
	s_cselect_b32 s99, s67, s71
	s_add_u32 s98, s98, s100
	s_addc_u32 s99, s99, 0
	v_lshlrev_b32_e32 v236, 4, v222
	global_store_dwordx4 v236, v[252:255], s[98:99] nt
	s_waitcnt vmcnt(0)
	v_readlane_b32 s88, v247, 23
	v_readlane_b32 s68, v247, 16
	v_readlane_b32 s72, v247, 26
	v_readlane_b32 s89, v247, 24
	v_readlane_b32 s69, v247, 17
	v_readlane_b32 s73, v247, 27
	s_barrier

.LBB0_1024:
	s_or_b64 exec, exec, s[0:1]
	s_mov_b32 s98, 0
	s_mov_b32 s99, 0
	s_mov_b32 s100, 0
	s_mov_b32 s101, 40
	v_lshlrev_b32_e32 v244, 4, v222
	v_mov_b32_e32 v8, v222
	s_waitcnt lgkmcnt(0)
	s_barrier
	s_and_b64 vcc, exec, s[72:73]
	v_readfirstlane_b32 s6, v8
	v_readlane_b32 s3, v247, 18
	s_cbranch_vccnz .LBB0_1027
	s_cmp_gt_i32 s3, 3
	s_cbranch_scc0 .LBB0_1113
	s_lshl_b32 s0, s3, 5
	s_or_b32 s2, s0, 4
	s_cbranch_execz .LBB0_1114
	s_branch .LBB0_1115

.LBB0_1030:
	s_add_u32 s42, s24, 0x1e04000
	s_addc_u32 s43, s25, 0
	s_add_i32 s5, s26, -16
	s_cmp_gt_i32 s88, 15
	s_cselect_b32 s5, s5, 0
	s_lshl_b32 s44, s0, 6
	s_lshl_b32 s7, s0, 13
	s_lshl_b32 s0, s1, 5
	s_and_b32 s45, s0, 0x60
	s_lshl_b32 s14, s45, 7
	s_add_u32 s10, s24, 0x1c20000
	s_mov_b64 s[12:13], 0x80
	s_addc_u32 s11, s25, 0
	s_add_i32 m0, s36, 0x18000
	v_lshl_add_u64 v[6:7], v[6:7], 0, s[12:13]
	s_waitcnt vmcnt(2)
	s_barrier
	global_load_lds_dwordx4 v[6:7], off
	v_lshl_add_u64 v[4:5], v[4:5], 0, s[12:13]
	s_add_i32 m0, s36, 0x1a000
	s_add_i32 s46, s36, 0x8000
	s_add_i32 s47, s36, 0xa000
	global_load_lds_dwordx4 v[4:5], off
	v_lshl_add_u64 v[2:3], v[2:3], 0, s[12:13]
	s_mov_b32 m0, s46
	s_add_u32 s0, s34, 0xb0080
	global_load_lds_dwordx4 v[2:3], off
	v_lshl_add_u64 v[0:1], v[0:1], 0, s[12:13]
	s_mov_b32 m0, s47
	s_addc_u32 s1, s35, 0
	global_load_lds_dwordx4 v[0:1], off
	s_add_i32 m0, s36, 0x1c000
	v_lshl_add_u64 v[0:1], s[0:1], 0, v[194:195]
	global_load_lds_dwordx4 v[0:1], off
	v_lshl_add_u64 v[0:1], s[0:1], 0, v[198:199]
	s_add_i32 m0, s36, 0x1e000
	v_bfe_u32 v227, v8, 4, 2
	global_load_lds_dwordx4 v[0:1], off
	v_and_b32_e32 v226, 15, v8
	v_lshlrev_b32_e32 v0, 4, v227
	v_lshlrev_b32_e32 v1, 2, v8
	v_lshl_or_b32 v0, v226, 6, v0
	v_and_b32_e32 v1, 32, v1
	s_cmpk_lt_u32 s6, 0x100
	v_bitop3_b32 v2, v0, s7, v1 bitop3:0xde
	v_bitop3_b32 v228, v0, s14, v1 bitop3:0xde
	s_cselect_b64 s[14:15], -1, 0
	v_and_b32_e32 v0, 63, v222
	s_cmp_gt_i32 s5, 0
	v_cmp_eq_u32_e64 s[0:1], 0, v0
	s_cselect_b64 s[6:7], -1, 0
	s_addk_i32 s64, 0x8000
	v_or_b32_e32 v0, 0x32f800, v222
	v_add_u32_e32 v229, s64, v0
	s_mov_b32 s16, 0x501000
	v_cmp_gt_i32_e32 vcc, s16, v229
	s_lshl_b32 s48, s5, 11
	v_lshrrev_b32_e32 v1, 1, v9
	v_mul_lo_u32 v0, v11, s4
	s_mov_b32 s5, 0xb000
	s_and_b64 s[16:17], s[6:7], vcc
	v_mad_u64_u32 v[0:1], s[6:7], v1, s5, v[0:1]
	v_or_b32_e32 v0, v0, v10
	s_mov_b64 s[18:19], 0xb0080
	v_add_lshl_u32 v0, v0, v12, 1
	v_mov_b32_e32 v1, v195
	v_lshl_add_u64 v[200:201], v[0:1], 0, s[18:19]
	v_lshrrev_b32_e32 v1, 1, v13
	v_mul_lo_u32 v0, v14, s4
	v_mad_u64_u32 v[0:1], s[4:5], v1, s5, v[0:1]
	s_waitcnt vmcnt(6)
	v_or_b32_e32 v0, v0, v15
	v_add_lshl_u32 v0, v0, v16, 1
	v_mov_b32_e32 v1, v195
	s_add_i32 s49, 0, 0x10000
	s_add_i32 s50, 0, 0x14000
	v_readlane_b32 s64, v247, 11
	v_lshl_add_u64 v[202:203], v[0:1], 0, s[18:19]
	v_mov_b64_e32 v[204:205], 0x104
	v_mov_b64_e32 v[206:207], 0x103
	v_add_u32_e32 v230, s49, v228
	v_add_u32_e32 v231, s50, v228
	v_add_u32_e32 v232, 0, v2
	s_movk_i32 s51, 0x3fff
	v_mbcnt_hi_u32_b32 v233, -1, v223
	s_mov_b32 s52, 0x80808081
	s_mov_b32 s53, 0xfffc0400
	s_mov_b32 s54, 0x500fff
	v_mov_b32_e32 v234, 0x358637bd
	v_readlane_b32 s65, v247, 12
	s_barrier
	s_branch .LBB0_1033

.LBB0_1032:
	s_mov_b32 s99, s98
	s_cmp_eq_u32 s99, 0
	s_cselect_b32 s101, 40, 8
	s_cmp_gt_u32 s99, 2
	s_cselect_b32 s101, 6, s101
	s_andn2_b64 vcc, exec, s[2:3]
	s_mov_b32 s58, s55
	s_mov_b32 s57, s56
	s_mov_b64 s[34:35], s[18:19]
	s_mov_b64 s[2:3], s[6:7]
	s_cbranch_vccz .LBB0_1112
.LBB0_1033:
	s_add_i32 s40, s40, 1
	s_mul_i32 s4, s40, s29
	s_mul_hi_u32 s5, s40, s28
	s_add_i32 s5, s5, s4
	s_mul_i32 s4, s40, s28
	s_add_u32 s4, s4, s88
	s_addc_u32 s5, s5, s89
	s_mov_b32 s98, 0
	s_mov_b32 s100, 0
	s_cmp_eq_u32 s40, 1
	s_cbranch_scc0 .Lks7_nosub
	s_cmp_lt_u32 s88, 16
	s_cbranch_scc0 .Lks7_nosub
	s_and_b32 s4, s88, 3
	s_add_i32 s4, s4, 0x100
	s_mov_b32 s5, 0
	s_lshr_b32 s100, s88, 2
	s_add_i32 s98, s100, 1
	s_mul_i32 s100, s100, 0x600
	s_cmp_eq_u32 s98, 4
	s_cselect_b32 s86, 0x100, 0
	s_sub_i32 s100, s100, s86
.Lks7_nosub:
	v_cmp_gt_i64_e32 vcc, s[4:5], v[206:207]
	v_cmp_lt_i64_e64 s[6:7], s[4:5], v[204:205]
	s_cbranch_vccnz .LBB0_1039
	s_ashr_i32 s5, s4, 31
	s_lshr_b32 s5, s5, 29
	s_add_i32 s18, s4, s5
	s_and_b32 s5, s18, -8
	s_sub_i32 s19, s4, s5
	s_cmp_gt_i32 s19, 3
	s_mov_b64 s[4:5], -1
	s_cbranch_scc0 .LBB0_1036
	s_lshl_b32 s4, s19, 5
	s_or_b32 s24, s4, 4
	s_mov_b64 s[4:5], 0

.LBB0_1039:
	s_nop 0
	v_cndmask_b32_e64 v0, 0, 1, s[6:7]
	v_cmp_ne_u32_e64 s[4:5], 1, v0
	s_andn2_b64 vcc, exec, s[6:7]
	s_mov_b64 s[6:7], s[2:3]
	s_cbranch_vccnz .LBB0_1041
	s_mul_i32 s6, s56, 0x160000
	s_mul_hi_i32 s7, s56, 0x160000
	s_add_u32 s6, s30, s6
	s_addc_u32 s7, s31, s7
	s_add_u32 s6, s6, s100
	s_addc_u32 s7, s7, 0
.LBB0_1041:
	s_and_b64 vcc, exec, s[4:5]
	s_mov_b64 s[18:19], s[34:35]
	s_cbranch_vccnz .LBB0_1043
	s_mul_i32 s18, s55, 0x160000
	s_mul_hi_i32 s19, s55, 0x160000
	s_add_u32 s18, s68, s18
	s_addc_u32 s19, s69, s19
	s_add_u32 s18, s18, s100
	s_addc_u32 s19, s19, 0

.LBB0_1044:
	ds_read_b128 v[128:131], v230
	ds_read_b128 v[132:135], v230 offset:1024
	ds_read_b128 v[136:139], v230 offset:2048
	ds_read_b128 v[140:143], v230 offset:3072
	ds_read_b128 v[144:147], v231
	ds_read_b128 v[148:151], v231 offset:1024
	ds_read_b128 v[152:155], v231 offset:2048
	ds_read_b128 v[156:159], v231 offset:3072
	s_add_u32 s24, s2, 0x100
	s_addc_u32 s25, s3, 0
	s_cmp_eq_u32 s61, s101
	s_cselect_b32 s35, s7, s25
	s_cselect_b32 s34, s6, s24
	s_cselect_b32 s27, s19, s60
	s_cselect_b32 s26, s18, s59
	v_lshl_add_u64 v[208:209], s[2:3], 0, v[200:201]
	s_add_i32 m0, s36, 0xc000
	ds_read_b128 v[160:163], v232
	ds_read_b128 v[164:167], v232 offset:1024
	ds_read_b128 v[168:171], v232 offset:2048
	ds_read_b128 v[172:175], v232 offset:3072
	ds_read_b128 v[176:179], v232 offset:4096
	ds_read_b128 v[180:183], v232 offset:5120
	ds_read_b128 v[184:187], v232 offset:6144
	ds_read_b128 v[188:191], v232 offset:7168
	global_load_lds_dwordx4 v[208:209], off
	v_lshl_add_u64 v[208:209], s[2:3], 0, v[202:203]
	s_add_i32 m0, s36, 0xe000
	s_nop 0
	global_load_lds_dwordx4 v[208:209], off
	s_waitcnt vmcnt(8)
	s_waitcnt lgkmcnt(0)
	s_barrier
	s_setprio 1
	s_waitcnt lgkmcnt(0)
	v_mfma_f32_16x16x32_bf16 v[124:127], v[128:131], v[160:163], v[124:127]
	v_mfma_f32_16x16x32_bf16 v[120:123], v[136:139], v[160:163], v[120:123]
	v_mfma_f32_16x16x32_bf16 v[108:111], v[128:131], v[168:171], v[108:111]
	v_mfma_f32_16x16x32_bf16 v[104:107], v[136:139], v[168:171], v[104:107]
	v_mfma_f32_16x16x32_bf16 v[92:95], v[128:131], v[176:179], v[92:95]
	v_mfma_f32_16x16x32_bf16 v[88:91], v[136:139], v[176:179], v[88:91]
	v_mfma_f32_16x16x32_bf16 v[76:79], v[128:131], v[184:187], v[76:79]
	v_mfma_f32_16x16x32_bf16 v[72:75], v[136:139], v[184:187], v[72:75]
	v_mfma_f32_16x16x32_bf16 v[124:127], v[132:135], v[164:167], v[124:127]
	v_mfma_f32_16x16x32_bf16 v[120:123], v[140:143], v[164:167], v[120:123]
	v_mfma_f32_16x16x32_bf16 v[108:111], v[132:135], v[172:175], v[108:111]
	v_mfma_f32_16x16x32_bf16 v[104:107], v[140:143], v[172:175], v[104:107]
	v_mfma_f32_16x16x32_bf16 v[92:95], v[132:135], v[180:183], v[92:95]
	v_mfma_f32_16x16x32_bf16 v[88:91], v[140:143], v[180:183], v[88:91]
	v_mfma_f32_16x16x32_bf16 v[76:79], v[132:135], v[188:191], v[76:79]
	v_mfma_f32_16x16x32_bf16 v[72:75], v[140:143], v[188:191], v[72:75]
	s_setprio 0
	s_setprio 1
	v_mfma_f32_16x16x32_bf16 v[116:119], v[144:147], v[160:163], v[116:119]
	v_mfma_f32_16x16x32_bf16 v[112:115], v[152:155], v[160:163], v[112:115]
	v_mfma_f32_16x16x32_bf16 v[100:103], v[144:147], v[168:171], v[100:103]
	v_mfma_f32_16x16x32_bf16 v[96:99], v[152:155], v[168:171], v[96:99]
	v_mfma_f32_16x16x32_bf16 v[84:87], v[144:147], v[176:179], v[84:87]
	v_mfma_f32_16x16x32_bf16 v[80:83], v[152:155], v[176:179], v[80:83]
	v_mfma_f32_16x16x32_bf16 v[68:71], v[144:147], v[184:187], v[68:71]
	v_mfma_f32_16x16x32_bf16 v[64:67], v[152:155], v[184:187], v[64:67]
	v_mfma_f32_16x16x32_bf16 v[116:119], v[148:151], v[164:167], v[116:119]
	v_mfma_f32_16x16x32_bf16 v[112:115], v[156:159], v[164:167], v[112:115]
	v_mfma_f32_16x16x32_bf16 v[100:103], v[148:151], v[172:175], v[100:103]
	v_mfma_f32_16x16x32_bf16 v[96:99], v[156:159], v[172:175], v[96:99]
	v_mfma_f32_16x16x32_bf16 v[84:87], v[148:151], v[180:183], v[84:87]
	v_mfma_f32_16x16x32_bf16 v[80:83], v[156:159], v[180:183], v[80:83]
	v_mfma_f32_16x16x32_bf16 v[68:71], v[148:151], v[188:191], v[68:71]
	v_mfma_f32_16x16x32_bf16 v[64:67], v[156:159], v[188:191], v[64:67]
	s_setprio 0
	s_barrier
	s_add_i32 s2, s49, s33
	v_lshl_add_u64 v[208:209], s[26:27], 0, v[194:195]
	s_mov_b32 m0, s2
	ds_read_b128 v[160:163], v232 offset:16384
	ds_read_b128 v[164:167], v232 offset:17408
	ds_read_b128 v[168:171], v232 offset:18432
	ds_read_b128 v[172:175], v232 offset:19456
	ds_read_b128 v[176:179], v232 offset:20480
	ds_read_b128 v[180:183], v232 offset:21504
	ds_read_b128 v[184:187], v232 offset:22528
	ds_read_b128 v[188:191], v232 offset:23552
	global_load_lds_dwordx4 v[208:209], off
	s_add_i32 m0, s2, 0x2000
	s_add_u32 s2, s26, 0xb0000
	v_lshl_add_u64 v[210:211], s[26:27], 0, v[198:199]
	s_addc_u32 s3, s27, 0
	s_add_i32 s62, s50, s33
	global_load_lds_dwordx4 v[210:211], off
	v_lshl_add_u64 v[212:213], s[2:3], 0, v[194:195]
	s_mov_b32 m0, s62
	v_lshl_add_u64 v[214:215], s[34:35], 0, v[196:197]
	global_load_lds_dwordx4 v[212:213], off
	v_lshl_add_u64 v[212:213], s[2:3], 0, v[198:199]
	s_add_i32 m0, s62, 0x2000
	s_nop 0
	global_load_lds_dwordx4 v[212:213], off
	v_lshl_add_u64 v[212:213], s[34:35], 0, v[192:193]
	s_mov_b32 m0, s36
	s_nop 0
	global_load_lds_dwordx4 v[212:213], off
	s_mov_b32 m0, s37
	s_nop 0
	global_load_lds_dwordx4 v[214:215], off
	s_waitcnt vmcnt(8)
	s_waitcnt lgkmcnt(0)
	s_barrier
	s_setprio 1
	s_waitcnt lgkmcnt(0)
	v_mfma_f32_16x16x32_bf16 v[60:63], v[128:131], v[160:163], v[60:63]
	v_mfma_f32_16x16x32_bf16 v[56:59], v[136:139], v[160:163], v[56:59]
	v_mfma_f32_16x16x32_bf16 v[44:47], v[128:131], v[168:171], v[44:47]
	v_mfma_f32_16x16x32_bf16 v[40:43], v[136:139], v[168:171], v[40:43]
	v_mfma_f32_16x16x32_bf16 v[28:31], v[128:131], v[176:179], v[28:31]
	v_mfma_f32_16x16x32_bf16 v[24:27], v[136:139], v[176:179], v[24:27]
	v_mfma_f32_16x16x32_bf16 v[12:15], v[128:131], v[184:187], v[12:15]
	v_mfma_f32_16x16x32_bf16 v[8:11], v[136:139], v[184:187], v[8:11]
	v_mfma_f32_16x16x32_bf16 v[60:63], v[132:135], v[164:167], v[60:63]
	v_mfma_f32_16x16x32_bf16 v[56:59], v[140:143], v[164:167], v[56:59]
	v_mfma_f32_16x16x32_bf16 v[44:47], v[132:135], v[172:175], v[44:47]
	v_mfma_f32_16x16x32_bf16 v[40:43], v[140:143], v[172:175], v[40:43]
	v_mfma_f32_16x16x32_bf16 v[28:31], v[132:135], v[180:183], v[28:31]
	v_mfma_f32_16x16x32_bf16 v[24:27], v[140:143], v[180:183], v[24:27]
	v_mfma_f32_16x16x32_bf16 v[12:15], v[132:135], v[188:191], v[12:15]
	v_mfma_f32_16x16x32_bf16 v[8:11], v[140:143], v[188:191], v[8:11]
	s_setprio 0
	s_setprio 1
	v_mfma_f32_16x16x32_bf16 v[52:55], v[144:147], v[160:163], v[52:55]
	v_mfma_f32_16x16x32_bf16 v[48:51], v[152:155], v[160:163], v[48:51]
	v_mfma_f32_16x16x32_bf16 v[36:39], v[144:147], v[168:171], v[36:39]
	v_mfma_f32_16x16x32_bf16 v[32:35], v[152:155], v[168:171], v[32:35]
	v_mfma_f32_16x16x32_bf16 v[20:23], v[144:147], v[176:179], v[20:23]
	v_mfma_f32_16x16x32_bf16 v[16:19], v[152:155], v[176:179], v[16:19]
	v_mfma_f32_16x16x32_bf16 v[4:7], v[144:147], v[184:187], v[4:7]
	v_mfma_f32_16x16x32_bf16 v[0:3], v[152:155], v[184:187], v[0:3]
	v_mfma_f32_16x16x32_bf16 v[52:55], v[148:151], v[164:167], v[52:55]
	v_mfma_f32_16x16x32_bf16 v[48:51], v[156:159], v[164:167], v[48:51]
	v_mfma_f32_16x16x32_bf16 v[36:39], v[148:151], v[172:175], v[36:39]
	v_mfma_f32_16x16x32_bf16 v[32:35], v[156:159], v[172:175], v[32:35]
	v_mfma_f32_16x16x32_bf16 v[20:23], v[148:151], v[180:183], v[20:23]
	v_mfma_f32_16x16x32_bf16 v[16:19], v[156:159], v[180:183], v[16:19]
	v_mfma_f32_16x16x32_bf16 v[4:7], v[148:151], v[188:191], v[4:7]
	v_mfma_f32_16x16x32_bf16 v[0:3], v[156:159], v[188:191], v[0:3]
	s_setprio 0
	s_barrier
	s_add_i32 s62, 0, 0x18000
	s_add_i32 s63, 0, 0x1c000
	v_add_u32_e32 v140, s62, v228
	v_add_u32_e32 v156, s63, v228
	ds_read_b128 v[128:131], v140
	ds_read_b128 v[132:135], v140 offset:1024
	ds_read_b128 v[136:139], v140 offset:2048
	ds_read_b128 v[140:143], v140 offset:3072
	ds_read_b128 v[144:147], v156
	ds_read_b128 v[148:151], v156 offset:1024
	ds_read_b128 v[152:155], v156 offset:2048
	ds_read_b128 v[156:159], v156 offset:3072
	s_add_u32 s2, s34, 0xb0000
	s_addc_u32 s3, s35, 0
	s_mov_b32 m0, s38
	v_lshl_add_u64 v[216:217], s[2:3], 0, v[192:193]
	ds_read_b128 v[160:163], v232 offset:32768
	ds_read_b128 v[164:167], v232 offset:33792
	ds_read_b128 v[168:171], v232 offset:34816
	ds_read_b128 v[172:175], v232 offset:35840
	ds_read_b128 v[176:179], v232 offset:36864
	ds_read_b128 v[180:183], v232 offset:37888
	ds_read_b128 v[184:187], v232 offset:38912
	ds_read_b128 v[188:191], v232 offset:39936
	global_load_lds_dwordx4 v[216:217], off
	v_lshl_add_u64 v[216:217], s[2:3], 0, v[196:197]
	s_mov_b32 m0, s39
	s_nop 0
	global_load_lds_dwordx4 v[216:217], off
	s_waitcnt vmcnt(8)
	s_waitcnt lgkmcnt(0)
	s_barrier
	s_setprio 1
	s_waitcnt lgkmcnt(0)
	v_mfma_f32_16x16x32_bf16 v[124:127], v[128:131], v[160:163], v[124:127]
	v_mfma_f32_16x16x32_bf16 v[120:123], v[136:139], v[160:163], v[120:123]
	v_mfma_f32_16x16x32_bf16 v[108:111], v[128:131], v[168:171], v[108:111]
	v_mfma_f32_16x16x32_bf16 v[104:107], v[136:139], v[168:171], v[104:107]
	v_mfma_f32_16x16x32_bf16 v[92:95], v[128:131], v[176:179], v[92:95]
	v_mfma_f32_16x16x32_bf16 v[88:91], v[136:139], v[176:179], v[88:91]
	v_mfma_f32_16x16x32_bf16 v[76:79], v[128:131], v[184:187], v[76:79]
	v_mfma_f32_16x16x32_bf16 v[72:75], v[136:139], v[184:187], v[72:75]
	v_mfma_f32_16x16x32_bf16 v[124:127], v[132:135], v[164:167], v[124:127]
	v_mfma_f32_16x16x32_bf16 v[120:123], v[140:143], v[164:167], v[120:123]
	v_mfma_f32_16x16x32_bf16 v[108:111], v[132:135], v[172:175], v[108:111]
	v_mfma_f32_16x16x32_bf16 v[104:107], v[140:143], v[172:175], v[104:107]
	v_mfma_f32_16x16x32_bf16 v[92:95], v[132:135], v[180:183], v[92:95]
	v_mfma_f32_16x16x32_bf16 v[88:91], v[140:143], v[180:183], v[88:91]
	v_mfma_f32_16x16x32_bf16 v[76:79], v[132:135], v[188:191], v[76:79]
	v_mfma_f32_16x16x32_bf16 v[72:75], v[140:143], v[188:191], v[72:75]
	s_setprio 0
	s_setprio 1
	v_mfma_f32_16x16x32_bf16 v[116:119], v[144:147], v[160:163], v[116:119]
	v_mfma_f32_16x16x32_bf16 v[112:115], v[152:155], v[160:163], v[112:115]
	v_mfma_f32_16x16x32_bf16 v[100:103], v[144:147], v[168:171], v[100:103]
	v_mfma_f32_16x16x32_bf16 v[96:99], v[152:155], v[168:171], v[96:99]
	v_mfma_f32_16x16x32_bf16 v[84:87], v[144:147], v[176:179], v[84:87]
	v_mfma_f32_16x16x32_bf16 v[80:83], v[152:155], v[176:179], v[80:83]
	v_mfma_f32_16x16x32_bf16 v[68:71], v[144:147], v[184:187], v[68:71]
	v_mfma_f32_16x16x32_bf16 v[64:67], v[152:155], v[184:187], v[64:67]
	v_mfma_f32_16x16x32_bf16 v[116:119], v[148:151], v[164:167], v[116:119]
	v_mfma_f32_16x16x32_bf16 v[112:115], v[156:159], v[164:167], v[112:115]
	v_mfma_f32_16x16x32_bf16 v[100:103], v[148:151], v[172:175], v[100:103]
	v_mfma_f32_16x16x32_bf16 v[96:99], v[156:159], v[172:175], v[96:99]
	v_mfma_f32_16x16x32_bf16 v[84:87], v[148:151], v[180:183], v[84:87]
	v_mfma_f32_16x16x32_bf16 v[80:83], v[156:159], v[180:183], v[80:83]
	v_mfma_f32_16x16x32_bf16 v[68:71], v[148:151], v[188:191], v[68:71]
	v_mfma_f32_16x16x32_bf16 v[64:67], v[156:159], v[188:191], v[64:67]
	s_setprio 0
	s_barrier
	s_add_i32 s2, s62, s33
	v_lshl_add_u64 v[208:209], v[208:209], 0, s[12:13]
	s_mov_b32 m0, s2
	ds_read_b128 v[160:163], v232 offset:49152
	ds_read_b128 v[164:167], v232 offset:50176
	ds_read_b128 v[168:171], v232 offset:51200
	ds_read_b128 v[172:175], v232 offset:52224
	ds_read_b128 v[176:179], v232 offset:53248
	ds_read_b128 v[180:183], v232 offset:54272
	ds_read_b128 v[184:187], v232 offset:55296
	ds_read_b128 v[188:191], v232 offset:56320
	global_load_lds_dwordx4 v[208:209], off
	s_add_i32 m0, s2, 0x2000
	s_add_u32 s2, s26, 0xb0080
	v_lshl_add_u64 v[208:209], v[210:211], 0, s[12:13]
	s_addc_u32 s3, s27, 0
	s_add_i32 s26, s63, s33
	global_load_lds_dwordx4 v[208:209], off
	v_lshl_add_u64 v[208:209], s[2:3], 0, v[194:195]
	s_mov_b32 m0, s26
	s_nop 0
	global_load_lds_dwordx4 v[208:209], off
	v_lshl_add_u64 v[208:209], s[2:3], 0, v[198:199]
	s_add_i32 m0, s26, 0x2000
	s_nop 0
	global_load_lds_dwordx4 v[208:209], off
	v_lshl_add_u64 v[208:209], v[212:213], 0, s[12:13]
	s_mov_b32 m0, s46
	s_nop 0
	global_load_lds_dwordx4 v[208:209], off
	v_lshl_add_u64 v[208:209], v[214:215], 0, s[12:13]
	s_mov_b32 m0, s47
	s_nop 0
	global_load_lds_dwordx4 v[208:209], off
	s_waitcnt vmcnt(8)
	s_waitcnt lgkmcnt(0)
	s_barrier
	s_setprio 1
	s_waitcnt lgkmcnt(0)
	v_mfma_f32_16x16x32_bf16 v[60:63], v[128:131], v[160:163], v[60:63]
	v_mfma_f32_16x16x32_bf16 v[56:59], v[136:139], v[160:163], v[56:59]
	v_mfma_f32_16x16x32_bf16 v[44:47], v[128:131], v[168:171], v[44:47]
	v_mfma_f32_16x16x32_bf16 v[40:43], v[136:139], v[168:171], v[40:43]
	v_mfma_f32_16x16x32_bf16 v[28:31], v[128:131], v[176:179], v[28:31]
	v_mfma_f32_16x16x32_bf16 v[24:27], v[136:139], v[176:179], v[24:27]
	v_mfma_f32_16x16x32_bf16 v[12:15], v[128:131], v[184:187], v[12:15]
	v_mfma_f32_16x16x32_bf16 v[8:11], v[136:139], v[184:187], v[8:11]
	v_mfma_f32_16x16x32_bf16 v[60:63], v[132:135], v[164:167], v[60:63]
	v_mfma_f32_16x16x32_bf16 v[56:59], v[140:143], v[164:167], v[56:59]
	v_mfma_f32_16x16x32_bf16 v[44:47], v[132:135], v[172:175], v[44:47]
	v_mfma_f32_16x16x32_bf16 v[40:43], v[140:143], v[172:175], v[40:43]
	v_mfma_f32_16x16x32_bf16 v[28:31], v[132:135], v[180:183], v[28:31]
	v_mfma_f32_16x16x32_bf16 v[24:27], v[140:143], v[180:183], v[24:27]
	v_mfma_f32_16x16x32_bf16 v[12:15], v[132:135], v[188:191], v[12:15]
	v_mfma_f32_16x16x32_bf16 v[8:11], v[140:143], v[188:191], v[8:11]
	s_setprio 0
	s_setprio 1
	v_mfma_f32_16x16x32_bf16 v[52:55], v[144:147], v[160:163], v[52:55]
	v_mfma_f32_16x16x32_bf16 v[48:51], v[152:155], v[160:163], v[48:51]
	v_mfma_f32_16x16x32_bf16 v[36:39], v[144:147], v[168:171], v[36:39]
	v_mfma_f32_16x16x32_bf16 v[32:35], v[152:155], v[168:171], v[32:35]
	v_mfma_f32_16x16x32_bf16 v[20:23], v[144:147], v[176:179], v[20:23]
	v_mfma_f32_16x16x32_bf16 v[16:19], v[152:155], v[176:179], v[16:19]
	v_mfma_f32_16x16x32_bf16 v[4:7], v[144:147], v[184:187], v[4:7]
	v_mfma_f32_16x16x32_bf16 v[0:3], v[152:155], v[184:187], v[0:3]
	v_mfma_f32_16x16x32_bf16 v[52:55], v[148:151], v[164:167], v[52:55]
	v_mfma_f32_16x16x32_bf16 v[48:51], v[156:159], v[164:167], v[48:51]
	v_mfma_f32_16x16x32_bf16 v[36:39], v[148:151], v[172:175], v[36:39]
	v_mfma_f32_16x16x32_bf16 v[32:35], v[156:159], v[172:175], v[32:35]
	v_mfma_f32_16x16x32_bf16 v[20:23], v[148:151], v[180:183], v[20:23]
	v_mfma_f32_16x16x32_bf16 v[16:19], v[156:159], v[180:183], v[16:19]
	v_mfma_f32_16x16x32_bf16 v[4:7], v[148:151], v[188:191], v[4:7]
	v_mfma_f32_16x16x32_bf16 v[0:3], v[156:159], v[188:191], v[0:3]
	s_setprio 0
	s_barrier
	s_add_i32 s61, s61, 2
	s_add_u32 s59, s59, 0x100
	s_addc_u32 s60, s60, 0
	s_cmp_gt_u32 s61, s101
	s_mov_b64 s[2:3], s[24:25]
	s_cbranch_scc0 .LBB0_1044
	s_and_b64 vcc, exec, s[14:15]
	s_cbranch_vccz .LBB0_1047
	s_barrier
.LBB0_1047:
	s_cmp_eq_u32 s99, 0
	s_cbranch_scc1 .Lks7_epi
	v_readlane_b32 s94, v247, 1
	v_readlane_b32 s95, v247, 2
	s_add_u32 s94, s94, 0x3900
	s_addc_u32 s95, s95, 0
	s_and_b32 s86, s88, 3
	s_lshl_b32 s86, s86, 6
	s_add_u32 s94, s94, s86
	s_addc_u32 s95, s95, 0
	v_readlane_b32 s92, v247, 1
	v_readlane_b32 s93, v247, 2
	s_add_u32 s92, s92, 0x10800000
	s_addc_u32 s93, s93, 0
	s_cmp_eq_u32 s99, 1
	s_cbranch_scc1 .Lks7_reduce
	s_sub_i32 s86, s88, 4
	s_lshl_b32 s86, s86, 18
	s_add_u32 s92, s92, s86
	s_addc_u32 s93, s93, 0
	global_store_dwordx4 v244, v[0:3], s[92:93]
	s_add_u32 s92, s92, 0x2000
	s_addc_u32 s93, s93, 0
	global_store_dwordx4 v244, v[4:7], s[92:93]
	s_add_u32 s92, s92, 0x2000
	s_addc_u32 s93, s93, 0
	global_store_dwordx4 v244, v[8:11], s[92:93]
	s_add_u32 s92, s92, 0x2000
	s_addc_u32 s93, s93, 0
	global_store_dwordx4 v244, v[12:15], s[92:93]
	s_add_u32 s92, s92, 0x2000
	s_addc_u32 s93, s93, 0
	global_store_dwordx4 v244, v[16:19], s[92:93]
	s_add_u32 s92, s92, 0x2000
	s_addc_u32 s93, s93, 0
	global_store_dwordx4 v244, v[20:23], s[92:93]
	s_add_u32 s92, s92, 0x2000
	s_addc_u32 s93, s93, 0
	global_store_dwordx4 v244, v[24:27], s[92:93]
	s_add_u32 s92, s92, 0x2000
	s_addc_u32 s93, s93, 0
	global_store_dwordx4 v244, v[28:31], s[92:93]
	s_add_u32 s92, s92, 0x2000
	s_addc_u32 s93, s93, 0
	global_store_dwordx4 v244, v[32:35], s[92:93]
	s_add_u32 s92, s92, 0x2000
	s_addc_u32 s93, s93, 0
	global_store_dwordx4 v244, v[36:39], s[92:93]
	s_add_u32 s92, s92, 0x2000
	s_addc_u32 s93, s93, 0
	global_store_dwordx4 v244, v[40:43], s[92:93]
	s_add_u32 s92, s92, 0x2000
	s_addc_u32 s93, s93, 0
	global_store_dwordx4 v244, v[44:47], s[92:93]
	s_add_u32 s92, s92, 0x2000
	s_addc_u32 s93, s93, 0
	global_store_dwordx4 v244, v[48:51], s[92:93]
	s_add_u32 s92, s92, 0x2000
	s_addc_u32 s93, s93, 0
	global_store_dwordx4 v244, v[52:55], s[92:93]
	s_add_u32 s92, s92, 0x2000
	s_addc_u32 s93, s93, 0
	global_store_dwordx4 v244, v[56:59], s[92:93]
	s_add_u32 s92, s92, 0x2000
	s_addc_u32 s93, s93, 0
	global_store_dwordx4 v244, v[60:63], s[92:93]
	s_add_u32 s92, s92, 0x2000
	s_addc_u32 s93, s93, 0
	global_store_dwordx4 v244, v[64:67], s[92:93]
	s_add_u32 s92, s92, 0x2000
	s_addc_u32 s93, s93, 0
	global_store_dwordx4 v244, v[68:71], s[92:93]
	s_add_u32 s92, s92, 0x2000
	s_addc_u32 s93, s93, 0
	global_store_dwordx4 v244, v[72:75], s[92:93]
	s_add_u32 s92, s92, 0x2000
	s_addc_u32 s93, s93, 0
	global_store_dwordx4 v244, v[76:79], s[92:93]
	s_add_u32 s92, s92, 0x2000
	s_addc_u32 s93, s93, 0
	global_store_dwordx4 v244, v[80:83], s[92:93]
	s_add_u32 s92, s92, 0x2000
	s_addc_u32 s93, s93, 0
	global_store_dwordx4 v244, v[84:87], s[92:93]
	s_add_u32 s92, s92, 0x2000
	s_addc_u32 s93, s93, 0
	global_store_dwordx4 v244, v[88:91], s[92:93]
	s_add_u32 s92, s92, 0x2000
	s_addc_u32 s93, s93, 0
	global_store_dwordx4 v244, v[92:95], s[92:93]
	s_add_u32 s92, s92, 0x2000
	s_addc_u32 s93, s93, 0
	global_store_dwordx4 v244, v[96:99], s[92:93]
	s_add_u32 s92, s92, 0x2000
	s_addc_u32 s93, s93, 0
	global_store_dwordx4 v244, v[100:103], s[92:93]
	s_add_u32 s92, s92, 0x2000
	s_addc_u32 s93, s93, 0
	global_store_dwordx4 v244, v[104:107], s[92:93]
	s_add_u32 s92, s92, 0x2000
	s_addc_u32 s93, s93, 0
	global_store_dwordx4 v244, v[108:111], s[92:93]
	s_add_u32 s92, s92, 0x2000
	s_addc_u32 s93, s93, 0
	global_store_dwordx4 v244, v[112:115], s[92:93]
	s_add_u32 s92, s92, 0x2000
	s_addc_u32 s93, s93, 0
	global_store_dwordx4 v244, v[116:119], s[92:93]
	s_add_u32 s92, s92, 0x2000
	s_addc_u32 s93, s93, 0
	global_store_dwordx4 v244, v[120:123], s[92:93]
	s_add_u32 s92, s92, 0x2000
	s_addc_u32 s93, s93, 0
	global_store_dwordx4 v244, v[124:127], s[92:93]
	s_add_u32 s92, s92, 0x2000
	s_addc_u32 s93, s93, 0
	s_waitcnt vmcnt(0)
	s_barrier
	v_cmp_eq_u32_e32 vcc, 0, v244
	s_and_saveexec_b64 s[96:97], vcc
	s_cbranch_execz .Lks7_nr_done
	buffer_wbl2 sc1
	s_waitcnt vmcnt(0)
	v_mov_b32_e32 v161, 0
	v_mov_b32_e32 v162, 1
	global_atomic_add v161, v162, s[94:95]
	s_waitcnt vmcnt(0)
.Lks7_nr_done:
	s_or_b64 exec, exec, s[96:97]
	s_mov_b64 s[2:3], -1
	s_branch .LBB0_1032
.Lks7_reduce:
	v_cmp_eq_u32_e32 vcc, 0, v244
	s_and_saveexec_b64 s[96:97], vcc
	s_cbranch_execz .Lks7_wait_done
	v_mov_b32_e32 v161, 0
	s_mov_b32 s86, 0
.Lks7_spin:
	global_load_dword v162, v161, s[94:95] sc1
	s_waitcnt vmcnt(0)
	v_readfirstlane_b32 s87, v162
	s_cmp_ge_u32 s87, 3
	s_cbranch_scc1 .Lks7_spin_done
	s_sleep 1
	s_add_i32 s86, s86, 1
	s_cmp_lt_u32 s86, 0x5000
	s_cbranch_scc1 .Lks7_spin

.Lks7_wait_done:
	s_or_b64 exec, exec, s[96:97]
	s_barrier
	s_lshl_b32 s86, s88, 18
	s_add_u32 s92, s92, s86
	s_addc_u32 s93, s93, 0
	global_load_dwordx4 v[128:131], v244, s[92:93]
	s_add_u32 s92, s92, 0x2000
	s_addc_u32 s93, s93, 0
	global_load_dwordx4 v[132:135], v244, s[92:93]
	s_add_u32 s92, s92, 0x2000
	s_addc_u32 s93, s93, 0
	global_load_dwordx4 v[136:139], v244, s[92:93]
	s_add_u32 s92, s92, 0x2000
	s_addc_u32 s93, s93, 0
	global_load_dwordx4 v[140:143], v244, s[92:93]
	s_add_u32 s92, s92, 0x2000
	s_addc_u32 s93, s93, 0
	global_load_dwordx4 v[144:147], v244, s[92:93]
	s_add_u32 s92, s92, 0x2000
	s_addc_u32 s93, s93, 0
	global_load_dwordx4 v[148:151], v244, s[92:93]
	s_add_u32 s92, s92, 0x2000
	s_addc_u32 s93, s93, 0
	global_load_dwordx4 v[152:155], v244, s[92:93]
	s_add_u32 s92, s92, 0x2000
	s_addc_u32 s93, s93, 0
	global_load_dwordx4 v[156:159], v244, s[92:93]
	s_add_u32 s92, s92, 0x2000
	s_addc_u32 s93, s93, 0
	s_waitcnt vmcnt(7)
	v_add_f32_e32 v0, v0, v128
	v_add_f32_e32 v1, v1, v129
	v_add_f32_e32 v2, v2, v130
	v_add_f32_e32 v3, v3, v131
	s_waitcnt vmcnt(6)
	v_add_f32_e32 v4, v4, v132
	v_add_f32_e32 v5, v5, v133
	v_add_f32_e32 v6, v6, v134
	v_add_f32_e32 v7, v7, v135
	s_waitcnt vmcnt(5)
	v_add_f32_e32 v8, v8, v136
	v_add_f32_e32 v9, v9, v137
	v_add_f32_e32 v10, v10, v138
	v_add_f32_e32 v11, v11, v139
	s_waitcnt vmcnt(4)
	v_add_f32_e32 v12, v12, v140
	v_add_f32_e32 v13, v13, v141
	v_add_f32_e32 v14, v14, v142
	v_add_f32_e32 v15, v15, v143
	s_waitcnt vmcnt(3)
	v_add_f32_e32 v16, v16, v144
	v_add_f32_e32 v17, v17, v145
	v_add_f32_e32 v18, v18, v146
	v_add_f32_e32 v19, v19, v147
	s_waitcnt vmcnt(2)
	v_add_f32_e32 v20, v20, v148
	v_add_f32_e32 v21, v21, v149
	v_add_f32_e32 v22, v22, v150
	v_add_f32_e32 v23, v23, v151
	s_waitcnt vmcnt(1)
	v_add_f32_e32 v24, v24, v152
	v_add_f32_e32 v25, v25, v153
	v_add_f32_e32 v26, v26, v154
	v_add_f32_e32 v27, v27, v155
	s_waitcnt vmcnt(0)
	v_add_f32_e32 v28, v28, v156
	v_add_f32_e32 v29, v29, v157
	v_add_f32_e32 v30, v30, v158
	v_add_f32_e32 v31, v31, v159
	global_load_dwordx4 v[128:131], v244, s[92:93]
	s_add_u32 s92, s92, 0x2000
	s_addc_u32 s93, s93, 0
	global_load_dwordx4 v[132:135], v244, s[92:93]
	s_add_u32 s92, s92, 0x2000
	s_addc_u32 s93, s93, 0
	global_load_dwordx4 v[136:139], v244, s[92:93]
	s_add_u32 s92, s92, 0x2000
	s_addc_u32 s93, s93, 0
	global_load_dwordx4 v[140:143], v244, s[92:93]
	s_add_u32 s92, s92, 0x2000
	s_addc_u32 s93, s93, 0
	global_load_dwordx4 v[144:147], v244, s[92:93]
	s_add_u32 s92, s92, 0x2000
	s_addc_u32 s93, s93, 0
	global_load_dwordx4 v[148:151], v244, s[92:93]
	s_add_u32 s92, s92, 0x2000
	s_addc_u32 s93, s93, 0
	global_load_dwordx4 v[152:155], v244, s[92:93]
	s_add_u32 s92, s92, 0x2000
	s_addc_u32 s93, s93, 0
	global_load_dwordx4 v[156:159], v244, s[92:93]
	s_add_u32 s92, s92, 0x2000
	s_addc_u32 s93, s93, 0
	s_waitcnt vmcnt(7)
	v_add_f32_e32 v32, v32, v128
	v_add_f32_e32 v33, v33, v129
	v_add_f32_e32 v34, v34, v130
	v_add_f32_e32 v35, v35, v131
	s_waitcnt vmcnt(6)
	v_add_f32_e32 v36, v36, v132
	v_add_f32_e32 v37, v37, v133
	v_add_f32_e32 v38, v38, v134
	v_add_f32_e32 v39, v39, v135
	s_waitcnt vmcnt(5)
	v_add_f32_e32 v40, v40, v136
	v_add_f32_e32 v41, v41, v137
	v_add_f32_e32 v42, v42, v138
	v_add_f32_e32 v43, v43, v139
	s_waitcnt vmcnt(4)
	v_add_f32_e32 v44, v44, v140
	v_add_f32_e32 v45, v45, v141
	v_add_f32_e32 v46, v46, v142
	v_add_f32_e32 v47, v47, v143
	s_waitcnt vmcnt(3)
	v_add_f32_e32 v48, v48, v144
	v_add_f32_e32 v49, v49, v145
	v_add_f32_e32 v50, v50, v146
	v_add_f32_e32 v51, v51, v147
	s_waitcnt vmcnt(2)
	v_add_f32_e32 v52, v52, v148
	v_add_f32_e32 v53, v53, v149
	v_add_f32_e32 v54, v54, v150
	v_add_f32_e32 v55, v55, v151
	s_waitcnt vmcnt(1)
	v_add_f32_e32 v56, v56, v152
	v_add_f32_e32 v57, v57, v153
	v_add_f32_e32 v58, v58, v154
	v_add_f32_e32 v59, v59, v155
	s_waitcnt vmcnt(0)
	v_add_f32_e32 v60, v60, v156
	v_add_f32_e32 v61, v61, v157
	v_add_f32_e32 v62, v62, v158
	v_add_f32_e32 v63, v63, v159
	global_load_dwordx4 v[128:131], v244, s[92:93]
	s_add_u32 s92, s92, 0x2000
	s_addc_u32 s93, s93, 0
	global_load_dwordx4 v[132:135], v244, s[92:93]
	s_add_u32 s92, s92, 0x2000
	s_addc_u32 s93, s93, 0
	global_load_dwordx4 v[136:139], v244, s[92:93]
	s_add_u32 s92, s92, 0x2000
	s_addc_u32 s93, s93, 0
	global_load_dwordx4 v[140:143], v244, s[92:93]
	s_add_u32 s92, s92, 0x2000
	s_addc_u32 s93, s93, 0
	global_load_dwordx4 v[144:147], v244, s[92:93]
	s_add_u32 s92, s92, 0x2000
	s_addc_u32 s93, s93, 0
	global_load_dwordx4 v[148:151], v244, s[92:93]
	s_add_u32 s92, s92, 0x2000
	s_addc_u32 s93, s93, 0
	global_load_dwordx4 v[152:155], v244, s[92:93]
	s_add_u32 s92, s92, 0x2000
	s_addc_u32 s93, s93, 0
	global_load_dwordx4 v[156:159], v244, s[92:93]
	s_add_u32 s92, s92, 0x2000
	s_addc_u32 s93, s93, 0
	s_waitcnt vmcnt(7)
	v_add_f32_e32 v64, v64, v128
	v_add_f32_e32 v65, v65, v129
	v_add_f32_e32 v66, v66, v130
	v_add_f32_e32 v67, v67, v131
	s_waitcnt vmcnt(6)
	v_add_f32_e32 v68, v68, v132
	v_add_f32_e32 v69, v69, v133
	v_add_f32_e32 v70, v70, v134
	v_add_f32_e32 v71, v71, v135
	s_waitcnt vmcnt(5)
	v_add_f32_e32 v72, v72, v136
	v_add_f32_e32 v73, v73, v137
	v_add_f32_e32 v74, v74, v138
	v_add_f32_e32 v75, v75, v139
	s_waitcnt vmcnt(4)
	v_add_f32_e32 v76, v76, v140
	v_add_f32_e32 v77, v77, v141
	v_add_f32_e32 v78, v78, v142
	v_add_f32_e32 v79, v79, v143
	s_waitcnt vmcnt(3)
	v_add_f32_e32 v80, v80, v144
	v_add_f32_e32 v81, v81, v145
	v_add_f32_e32 v82, v82, v146
	v_add_f32_e32 v83, v83, v147
	s_waitcnt vmcnt(2)
	v_add_f32_e32 v84, v84, v148
	v_add_f32_e32 v85, v85, v149
	v_add_f32_e32 v86, v86, v150
	v_add_f32_e32 v87, v87, v151
	s_waitcnt vmcnt(1)
	v_add_f32_e32 v88, v88, v152
	v_add_f32_e32 v89, v89, v153
	v_add_f32_e32 v90, v90, v154
	v_add_f32_e32 v91, v91, v155
	s_waitcnt vmcnt(0)
	v_add_f32_e32 v92, v92, v156
	v_add_f32_e32 v93, v93, v157
	v_add_f32_e32 v94, v94, v158
	v_add_f32_e32 v95, v95, v159
	global_load_dwordx4 v[128:131], v244, s[92:93]
	s_add_u32 s92, s92, 0x2000
	s_addc_u32 s93, s93, 0
	global_load_dwordx4 v[132:135], v244, s[92:93]
	s_add_u32 s92, s92, 0x2000
	s_addc_u32 s93, s93, 0
	global_load_dwordx4 v[136:139], v244, s[92:93]
	s_add_u32 s92, s92, 0x2000
	s_addc_u32 s93, s93, 0
	global_load_dwordx4 v[140:143], v244, s[92:93]
	s_add_u32 s92, s92, 0x2000
	s_addc_u32 s93, s93, 0
	global_load_dwordx4 v[144:147], v244, s[92:93]
	s_add_u32 s92, s92, 0x2000
	s_addc_u32 s93, s93, 0
	global_load_dwordx4 v[148:151], v244, s[92:93]
	s_add_u32 s92, s92, 0x2000
	s_addc_u32 s93, s93, 0
	global_load_dwordx4 v[152:155], v244, s[92:93]
	s_add_u32 s92, s92, 0x2000
	s_addc_u32 s93, s93, 0
	global_load_dwordx4 v[156:159], v244, s[92:93]
	s_add_u32 s92, s92, 0x2000
	s_addc_u32 s93, s93, 0
	s_waitcnt vmcnt(7)
	v_add_f32_e32 v96, v96, v128
	v_add_f32_e32 v97, v97, v129
	v_add_f32_e32 v98, v98, v130
	v_add_f32_e32 v99, v99, v131
	s_waitcnt vmcnt(6)
	v_add_f32_e32 v100, v100, v132
	v_add_f32_e32 v101, v101, v133
	v_add_f32_e32 v102, v102, v134
	v_add_f32_e32 v103, v103, v135
	s_waitcnt vmcnt(5)
	v_add_f32_e32 v104, v104, v136
	v_add_f32_e32 v105, v105, v137
	v_add_f32_e32 v106, v106, v138
	v_add_f32_e32 v107, v107, v139
	s_waitcnt vmcnt(4)
	v_add_f32_e32 v108, v108, v140
	v_add_f32_e32 v109, v109, v141
	v_add_f32_e32 v110, v110, v142
	v_add_f32_e32 v111, v111, v143
	s_waitcnt vmcnt(3)
	v_add_f32_e32 v112, v112, v144
	v_add_f32_e32 v113, v113, v145
	v_add_f32_e32 v114, v114, v146
	v_add_f32_e32 v115, v115, v147
	s_waitcnt vmcnt(2)
	v_add_f32_e32 v116, v116, v148
	v_add_f32_e32 v117, v117, v149
	v_add_f32_e32 v118, v118, v150
	v_add_f32_e32 v119, v119, v151
	s_waitcnt vmcnt(1)
	v_add_f32_e32 v120, v120, v152
	v_add_f32_e32 v121, v121, v153
	v_add_f32_e32 v122, v122, v154
	v_add_f32_e32 v123, v123, v155
	s_waitcnt vmcnt(0)
	v_add_f32_e32 v124, v124, v156
	v_add_f32_e32 v125, v125, v157
	v_add_f32_e32 v126, v126, v158
	v_add_f32_e32 v127, v127, v159
	s_add_u32 s92, s92, 0xc0000
	s_addc_u32 s93, s93, 0
	global_load_dwordx4 v[128:131], v244, s[92:93]
	s_add_u32 s92, s92, 0x2000
	s_addc_u32 s93, s93, 0
	global_load_dwordx4 v[132:135], v244, s[92:93]
	s_add_u32 s92, s92, 0x2000
	s_addc_u32 s93, s93, 0
	global_load_dwordx4 v[136:139], v244, s[92:93]
	s_add_u32 s92, s92, 0x2000
	s_addc_u32 s93, s93, 0
	global_load_dwordx4 v[140:143], v244, s[92:93]
	s_add_u32 s92, s92, 0x2000
	s_addc_u32 s93, s93, 0
	global_load_dwordx4 v[144:147], v244, s[92:93]
	s_add_u32 s92, s92, 0x2000
	s_addc_u32 s93, s93, 0
	global_load_dwordx4 v[148:151], v244, s[92:93]
	s_add_u32 s92, s92, 0x2000
	s_addc_u32 s93, s93, 0
	global_load_dwordx4 v[152:155], v244, s[92:93]
	s_add_u32 s92, s92, 0x2000
	s_addc_u32 s93, s93, 0
	global_load_dwordx4 v[156:159], v244, s[92:93]
	s_add_u32 s92, s92, 0x2000
	s_addc_u32 s93, s93, 0
	s_waitcnt vmcnt(7)
	v_add_f32_e32 v0, v0, v128
	v_add_f32_e32 v1, v1, v129
	v_add_f32_e32 v2, v2, v130
	v_add_f32_e32 v3, v3, v131
	s_waitcnt vmcnt(6)
	v_add_f32_e32 v4, v4, v132
	v_add_f32_e32 v5, v5, v133
	v_add_f32_e32 v6, v6, v134
	v_add_f32_e32 v7, v7, v135
	s_waitcnt vmcnt(5)
	v_add_f32_e32 v8, v8, v136
	v_add_f32_e32 v9, v9, v137
	v_add_f32_e32 v10, v10, v138
	v_add_f32_e32 v11, v11, v139
	s_waitcnt vmcnt(4)
	v_add_f32_e32 v12, v12, v140
	v_add_f32_e32 v13, v13, v141
	v_add_f32_e32 v14, v14, v142
	v_add_f32_e32 v15, v15, v143
	s_waitcnt vmcnt(3)
	v_add_f32_e32 v16, v16, v144
	v_add_f32_e32 v17, v17, v145
	v_add_f32_e32 v18, v18, v146
	v_add_f32_e32 v19, v19, v147
	s_waitcnt vmcnt(2)
	v_add_f32_e32 v20, v20, v148
	v_add_f32_e32 v21, v21, v149
	v_add_f32_e32 v22, v22, v150
	v_add_f32_e32 v23, v23, v151
	s_waitcnt vmcnt(1)
	v_add_f32_e32 v24, v24, v152
	v_add_f32_e32 v25, v25, v153
	v_add_f32_e32 v26, v26, v154
	v_add_f32_e32 v27, v27, v155
	s_waitcnt vmcnt(0)
	v_add_f32_e32 v28, v28, v156
	v_add_f32_e32 v29, v29, v157
	v_add_f32_e32 v30, v30, v158
	v_add_f32_e32 v31, v31, v159
	global_load_dwordx4 v[128:131], v244, s[92:93]
	s_add_u32 s92, s92, 0x2000
	s_addc_u32 s93, s93, 0
	global_load_dwordx4 v[132:135], v244, s[92:93]
	s_add_u32 s92, s92, 0x2000
	s_addc_u32 s93, s93, 0
	global_load_dwordx4 v[136:139], v244, s[92:93]
	s_add_u32 s92, s92, 0x2000
	s_addc_u32 s93, s93, 0
	global_load_dwordx4 v[140:143], v244, s[92:93]
	s_add_u32 s92, s92, 0x2000
	s_addc_u32 s93, s93, 0
	global_load_dwordx4 v[144:147], v244, s[92:93]
	s_add_u32 s92, s92, 0x2000
	s_addc_u32 s93, s93, 0
	global_load_dwordx4 v[148:151], v244, s[92:93]
	s_add_u32 s92, s92, 0x2000
	s_addc_u32 s93, s93, 0
	global_load_dwordx4 v[152:155], v244, s[92:93]
	s_add_u32 s92, s92, 0x2000
	s_addc_u32 s93, s93, 0
	global_load_dwordx4 v[156:159], v244, s[92:93]
	s_add_u32 s92, s92, 0x2000
	s_addc_u32 s93, s93, 0
	s_waitcnt vmcnt(7)
	v_add_f32_e32 v32, v32, v128
	v_add_f32_e32 v33, v33, v129
	v_add_f32_e32 v34, v34, v130
	v_add_f32_e32 v35, v35, v131
	s_waitcnt vmcnt(6)
	v_add_f32_e32 v36, v36, v132
	v_add_f32_e32 v37, v37, v133
	v_add_f32_e32 v38, v38, v134
	v_add_f32_e32 v39, v39, v135
	s_waitcnt vmcnt(5)
	v_add_f32_e32 v40, v40, v136
	v_add_f32_e32 v41, v41, v137
	v_add_f32_e32 v42, v42, v138
	v_add_f32_e32 v43, v43, v139
	s_waitcnt vmcnt(4)
	v_add_f32_e32 v44, v44, v140
	v_add_f32_e32 v45, v45, v141
	v_add_f32_e32 v46, v46, v142
	v_add_f32_e32 v47, v47, v143
	s_waitcnt vmcnt(3)
	v_add_f32_e32 v48, v48, v144
	v_add_f32_e32 v49, v49, v145
	v_add_f32_e32 v50, v50, v146
	v_add_f32_e32 v51, v51, v147
	s_waitcnt vmcnt(2)
	v_add_f32_e32 v52, v52, v148
	v_add_f32_e32 v53, v53, v149
	v_add_f32_e32 v54, v54, v150
	v_add_f32_e32 v55, v55, v151
	s_waitcnt vmcnt(1)
	v_add_f32_e32 v56, v56, v152
	v_add_f32_e32 v57, v57, v153
	v_add_f32_e32 v58, v58, v154
	v_add_f32_e32 v59, v59, v155
	s_waitcnt vmcnt(0)
	v_add_f32_e32 v60, v60, v156
	v_add_f32_e32 v61, v61, v157
	v_add_f32_e32 v62, v62, v158
	v_add_f32_e32 v63, v63, v159
	global_load_dwordx4 v[128:131], v244, s[92:93]
	s_add_u32 s92, s92, 0x2000
	s_addc_u32 s93, s93, 0
	global_load_dwordx4 v[132:135], v244, s[92:93]
	s_add_u32 s92, s92, 0x2000
	s_addc_u32 s93, s93, 0
	global_load_dwordx4 v[136:139], v244, s[92:93]
	s_add_u32 s92, s92, 0x2000
	s_addc_u32 s93, s93, 0
	global_load_dwordx4 v[140:143], v244, s[92:93]
	s_add_u32 s92, s92, 0x2000
	s_addc_u32 s93, s93, 0
	global_load_dwordx4 v[144:147], v244, s[92:93]
	s_add_u32 s92, s92, 0x2000
	s_addc_u32 s93, s93, 0
	global_load_dwordx4 v[148:151], v244, s[92:93]
	s_add_u32 s92, s92, 0x2000
	s_addc_u32 s93, s93, 0
	global_load_dwordx4 v[152:155], v244, s[92:93]
	s_add_u32 s92, s92, 0x2000
	s_addc_u32 s93, s93, 0
	global_load_dwordx4 v[156:159], v244, s[92:93]
	s_add_u32 s92, s92, 0x2000
	s_addc_u32 s93, s93, 0
	s_waitcnt vmcnt(7)
	v_add_f32_e32 v64, v64, v128
	v_add_f32_e32 v65, v65, v129
	v_add_f32_e32 v66, v66, v130
	v_add_f32_e32 v67, v67, v131
	s_waitcnt vmcnt(6)
	v_add_f32_e32 v68, v68, v132
	v_add_f32_e32 v69, v69, v133
	v_add_f32_e32 v70, v70, v134
	v_add_f32_e32 v71, v71, v135
	s_waitcnt vmcnt(5)
	v_add_f32_e32 v72, v72, v136
	v_add_f32_e32 v73, v73, v137
	v_add_f32_e32 v74, v74, v138
	v_add_f32_e32 v75, v75, v139
	s_waitcnt vmcnt(4)
	v_add_f32_e32 v76, v76, v140
	v_add_f32_e32 v77, v77, v141
	v_add_f32_e32 v78, v78, v142
	v_add_f32_e32 v79, v79, v143
	s_waitcnt vmcnt(3)
	v_add_f32_e32 v80, v80, v144
	v_add_f32_e32 v81, v81, v145
	v_add_f32_e32 v82, v82, v146
	v_add_f32_e32 v83, v83, v147
	s_waitcnt vmcnt(2)
	v_add_f32_e32 v84, v84, v148
	v_add_f32_e32 v85, v85, v149
	v_add_f32_e32 v86, v86, v150
	v_add_f32_e32 v87, v87, v151
	s_waitcnt vmcnt(1)
	v_add_f32_e32 v88, v88, v152
	v_add_f32_e32 v89, v89, v153
	v_add_f32_e32 v90, v90, v154
	v_add_f32_e32 v91, v91, v155
	s_waitcnt vmcnt(0)
	v_add_f32_e32 v92, v92, v156
	v_add_f32_e32 v93, v93, v157
	v_add_f32_e32 v94, v94, v158
	v_add_f32_e32 v95, v95, v159
	global_load_dwordx4 v[128:131], v244, s[92:93]
	s_add_u32 s92, s92, 0x2000
	s_addc_u32 s93, s93, 0
	global_load_dwordx4 v[132:135], v244, s[92:93]
	s_add_u32 s92, s92, 0x2000
	s_addc_u32 s93, s93, 0
	global_load_dwordx4 v[136:139], v244, s[92:93]
	s_add_u32 s92, s92, 0x2000
	s_addc_u32 s93, s93, 0
	global_load_dwordx4 v[140:143], v244, s[92:93]
	s_add_u32 s92, s92, 0x2000
	s_addc_u32 s93, s93, 0
	global_load_dwordx4 v[144:147], v244, s[92:93]
	s_add_u32 s92, s92, 0x2000
	s_addc_u32 s93, s93, 0
	global_load_dwordx4 v[148:151], v244, s[92:93]
	s_add_u32 s92, s92, 0x2000
	s_addc_u32 s93, s93, 0
	global_load_dwordx4 v[152:155], v244, s[92:93]
	s_add_u32 s92, s92, 0x2000
	s_addc_u32 s93, s93, 0
	global_load_dwordx4 v[156:159], v244, s[92:93]
	s_add_u32 s92, s92, 0x2000
	s_addc_u32 s93, s93, 0
	s_waitcnt vmcnt(7)
	v_add_f32_e32 v96, v96, v128
	v_add_f32_e32 v97, v97, v129
	v_add_f32_e32 v98, v98, v130
	v_add_f32_e32 v99, v99, v131
	s_waitcnt vmcnt(6)
	v_add_f32_e32 v100, v100, v132
	v_add_f32_e32 v101, v101, v133
	v_add_f32_e32 v102, v102, v134
	v_add_f32_e32 v103, v103, v135
	s_waitcnt vmcnt(5)
	v_add_f32_e32 v104, v104, v136
	v_add_f32_e32 v105, v105, v137
	v_add_f32_e32 v106, v106, v138
	v_add_f32_e32 v107, v107, v139
	s_waitcnt vmcnt(4)
	v_add_f32_e32 v108, v108, v140
	v_add_f32_e32 v109, v109, v141
	v_add_f32_e32 v110, v110, v142
	v_add_f32_e32 v111, v111, v143
	s_waitcnt vmcnt(3)
	v_add_f32_e32 v112, v112, v144
	v_add_f32_e32 v113, v113, v145
	v_add_f32_e32 v114, v114, v146
	v_add_f32_e32 v115, v115, v147
	s_waitcnt vmcnt(2)
	v_add_f32_e32 v116, v116, v148
	v_add_f32_e32 v117, v117, v149
	v_add_f32_e32 v118, v118, v150
	v_add_f32_e32 v119, v119, v151
	s_waitcnt vmcnt(1)
	v_add_f32_e32 v120, v120, v152
	v_add_f32_e32 v121, v121, v153
	v_add_f32_e32 v122, v122, v154
	v_add_f32_e32 v123, v123, v155
	s_waitcnt vmcnt(0)
	v_add_f32_e32 v124, v124, v156
	v_add_f32_e32 v125, v125, v157
	v_add_f32_e32 v126, v126, v158
	v_add_f32_e32 v127, v127, v159
	s_add_u32 s92, s92, 0xc0000
	s_addc_u32 s93, s93, 0
	global_load_dwordx4 v[128:131], v244, s[92:93]
	s_add_u32 s92, s92, 0x2000
	s_addc_u32 s93, s93, 0
	global_load_dwordx4 v[132:135], v244, s[92:93]
	s_add_u32 s92, s92, 0x2000
	s_addc_u32 s93, s93, 0
	global_load_dwordx4 v[136:139], v244, s[92:93]
	s_add_u32 s92, s92, 0x2000
	s_addc_u32 s93, s93, 0
	global_load_dwordx4 v[140:143], v244, s[92:93]
	s_add_u32 s92, s92, 0x2000
	s_addc_u32 s93, s93, 0
	global_load_dwordx4 v[144:147], v244, s[92:93]
	s_add_u32 s92, s92, 0x2000
	s_addc_u32 s93, s93, 0
	global_load_dwordx4 v[148:151], v244, s[92:93]
	s_add_u32 s92, s92, 0x2000
	s_addc_u32 s93, s93, 0
	global_load_dwordx4 v[152:155], v244, s[92:93]
	s_add_u32 s92, s92, 0x2000
	s_addc_u32 s93, s93, 0
	global_load_dwordx4 v[156:159], v244, s[92:93]
	s_add_u32 s92, s92, 0x2000
	s_addc_u32 s93, s93, 0
	s_waitcnt vmcnt(7)
	v_add_f32_e32 v0, v0, v128
	v_add_f32_e32 v1, v1, v129
	v_add_f32_e32 v2, v2, v130
	v_add_f32_e32 v3, v3, v131
	s_waitcnt vmcnt(6)
	v_add_f32_e32 v4, v4, v132
	v_add_f32_e32 v5, v5, v133
	v_add_f32_e32 v6, v6, v134
	v_add_f32_e32 v7, v7, v135
	s_waitcnt vmcnt(5)
	v_add_f32_e32 v8, v8, v136
	v_add_f32_e32 v9, v9, v137
	v_add_f32_e32 v10, v10, v138
	v_add_f32_e32 v11, v11, v139
	s_waitcnt vmcnt(4)
	v_add_f32_e32 v12, v12, v140
	v_add_f32_e32 v13, v13, v141
	v_add_f32_e32 v14, v14, v142
	v_add_f32_e32 v15, v15, v143
	s_waitcnt vmcnt(3)
	v_add_f32_e32 v16, v16, v144
	v_add_f32_e32 v17, v17, v145
	v_add_f32_e32 v18, v18, v146
	v_add_f32_e32 v19, v19, v147
	s_waitcnt vmcnt(2)
	v_add_f32_e32 v20, v20, v148
	v_add_f32_e32 v21, v21, v149
	v_add_f32_e32 v22, v22, v150
	v_add_f32_e32 v23, v23, v151
	s_waitcnt vmcnt(1)
	v_add_f32_e32 v24, v24, v152
	v_add_f32_e32 v25, v25, v153
	v_add_f32_e32 v26, v26, v154
	v_add_f32_e32 v27, v27, v155
	s_waitcnt vmcnt(0)
	v_add_f32_e32 v28, v28, v156
	v_add_f32_e32 v29, v29, v157
	v_add_f32_e32 v30, v30, v158
	v_add_f32_e32 v31, v31, v159
	global_load_dwordx4 v[128:131], v244, s[92:93]
	s_add_u32 s92, s92, 0x2000
	s_addc_u32 s93, s93, 0
	global_load_dwordx4 v[132:135], v244, s[92:93]
	s_add_u32 s92, s92, 0x2000
	s_addc_u32 s93, s93, 0
	global_load_dwordx4 v[136:139], v244, s[92:93]
	s_add_u32 s92, s92, 0x2000
	s_addc_u32 s93, s93, 0
	global_load_dwordx4 v[140:143], v244, s[92:93]
	s_add_u32 s92, s92, 0x2000
	s_addc_u32 s93, s93, 0
	global_load_dwordx4 v[144:147], v244, s[92:93]
	s_add_u32 s92, s92, 0x2000
	s_addc_u32 s93, s93, 0
	global_load_dwordx4 v[148:151], v244, s[92:93]
	s_add_u32 s92, s92, 0x2000
	s_addc_u32 s93, s93, 0
	global_load_dwordx4 v[152:155], v244, s[92:93]
	s_add_u32 s92, s92, 0x2000
	s_addc_u32 s93, s93, 0
	global_load_dwordx4 v[156:159], v244, s[92:93]
	s_add_u32 s92, s92, 0x2000
	s_addc_u32 s93, s93, 0
	s_waitcnt vmcnt(7)
	v_add_f32_e32 v32, v32, v128
	v_add_f32_e32 v33, v33, v129
	v_add_f32_e32 v34, v34, v130
	v_add_f32_e32 v35, v35, v131
	s_waitcnt vmcnt(6)
	v_add_f32_e32 v36, v36, v132
	v_add_f32_e32 v37, v37, v133
	v_add_f32_e32 v38, v38, v134
	v_add_f32_e32 v39, v39, v135
	s_waitcnt vmcnt(5)
	v_add_f32_e32 v40, v40, v136
	v_add_f32_e32 v41, v41, v137
	v_add_f32_e32 v42, v42, v138
	v_add_f32_e32 v43, v43, v139
	s_waitcnt vmcnt(4)
	v_add_f32_e32 v44, v44, v140
	v_add_f32_e32 v45, v45, v141
	v_add_f32_e32 v46, v46, v142
	v_add_f32_e32 v47, v47, v143
	s_waitcnt vmcnt(3)
	v_add_f32_e32 v48, v48, v144
	v_add_f32_e32 v49, v49, v145
	v_add_f32_e32 v50, v50, v146
	v_add_f32_e32 v51, v51, v147
	s_waitcnt vmcnt(2)
	v_add_f32_e32 v52, v52, v148
	v_add_f32_e32 v53, v53, v149
	v_add_f32_e32 v54, v54, v150
	v_add_f32_e32 v55, v55, v151
	s_waitcnt vmcnt(1)
	v_add_f32_e32 v56, v56, v152
	v_add_f32_e32 v57, v57, v153
	v_add_f32_e32 v58, v58, v154
	v_add_f32_e32 v59, v59, v155
	s_waitcnt vmcnt(0)
	v_add_f32_e32 v60, v60, v156
	v_add_f32_e32 v61, v61, v157
	v_add_f32_e32 v62, v62, v158
	v_add_f32_e32 v63, v63, v159
	global_load_dwordx4 v[128:131], v244, s[92:93]
	s_add_u32 s92, s92, 0x2000
	s_addc_u32 s93, s93, 0
	global_load_dwordx4 v[132:135], v244, s[92:93]
	s_add_u32 s92, s92, 0x2000
	s_addc_u32 s93, s93, 0
	global_load_dwordx4 v[136:139], v244, s[92:93]
	s_add_u32 s92, s92, 0x2000
	s_addc_u32 s93, s93, 0
	global_load_dwordx4 v[140:143], v244, s[92:93]
	s_add_u32 s92, s92, 0x2000
	s_addc_u32 s93, s93, 0
	global_load_dwordx4 v[144:147], v244, s[92:93]
	s_add_u32 s92, s92, 0x2000
	s_addc_u32 s93, s93, 0
	global_load_dwordx4 v[148:151], v244, s[92:93]
	s_add_u32 s92, s92, 0x2000
	s_addc_u32 s93, s93, 0
	global_load_dwordx4 v[152:155], v244, s[92:93]
	s_add_u32 s92, s92, 0x2000
	s_addc_u32 s93, s93, 0
	global_load_dwordx4 v[156:159], v244, s[92:93]
	s_add_u32 s92, s92, 0x2000
	s_addc_u32 s93, s93, 0
	s_waitcnt vmcnt(7)
	v_add_f32_e32 v64, v64, v128
	v_add_f32_e32 v65, v65, v129
	v_add_f32_e32 v66, v66, v130
	v_add_f32_e32 v67, v67, v131
	s_waitcnt vmcnt(6)
	v_add_f32_e32 v68, v68, v132
	v_add_f32_e32 v69, v69, v133
	v_add_f32_e32 v70, v70, v134
	v_add_f32_e32 v71, v71, v135
	s_waitcnt vmcnt(5)
	v_add_f32_e32 v72, v72, v136
	v_add_f32_e32 v73, v73, v137
	v_add_f32_e32 v74, v74, v138
	v_add_f32_e32 v75, v75, v139
	s_waitcnt vmcnt(4)
	v_add_f32_e32 v76, v76, v140
	v_add_f32_e32 v77, v77, v141
	v_add_f32_e32 v78, v78, v142
	v_add_f32_e32 v79, v79, v143
	s_waitcnt vmcnt(3)
	v_add_f32_e32 v80, v80, v144
	v_add_f32_e32 v81, v81, v145
	v_add_f32_e32 v82, v82, v146
	v_add_f32_e32 v83, v83, v147
	s_waitcnt vmcnt(2)
	v_add_f32_e32 v84, v84, v148
	v_add_f32_e32 v85, v85, v149
	v_add_f32_e32 v86, v86, v150
	v_add_f32_e32 v87, v87, v151
	s_waitcnt vmcnt(1)
	v_add_f32_e32 v88, v88, v152
	v_add_f32_e32 v89, v89, v153
	v_add_f32_e32 v90, v90, v154
	v_add_f32_e32 v91, v91, v155
	s_waitcnt vmcnt(0)
	v_add_f32_e32 v92, v92, v156
	v_add_f32_e32 v93, v93, v157
	v_add_f32_e32 v94, v94, v158
	v_add_f32_e32 v95, v95, v159
	global_load_dwordx4 v[128:131], v244, s[92:93]
	s_add_u32 s92, s92, 0x2000
	s_addc_u32 s93, s93, 0
	global_load_dwordx4 v[132:135], v244, s[92:93]
	s_add_u32 s92, s92, 0x2000
	s_addc_u32 s93, s93, 0
	global_load_dwordx4 v[136:139], v244, s[92:93]
	s_add_u32 s92, s92, 0x2000
	s_addc_u32 s93, s93, 0
	global_load_dwordx4 v[140:143], v244, s[92:93]
	s_add_u32 s92, s92, 0x2000
	s_addc_u32 s93, s93, 0
	global_load_dwordx4 v[144:147], v244, s[92:93]
	s_add_u32 s92, s92, 0x2000
	s_addc_u32 s93, s93, 0
	global_load_dwordx4 v[148:151], v244, s[92:93]
	s_add_u32 s92, s92, 0x2000
	s_addc_u32 s93, s93, 0
	global_load_dwordx4 v[152:155], v244, s[92:93]
	s_add_u32 s92, s92, 0x2000
	s_addc_u32 s93, s93, 0
	global_load_dwordx4 v[156:159], v244, s[92:93]
	s_add_u32 s92, s92, 0x2000
	s_addc_u32 s93, s93, 0
	s_waitcnt vmcnt(7)
	v_add_f32_e32 v96, v96, v128
	v_add_f32_e32 v97, v97, v129
	v_add_f32_e32 v98, v98, v130
	v_add_f32_e32 v99, v99, v131
	s_waitcnt vmcnt(6)
	v_add_f32_e32 v100, v100, v132
	v_add_f32_e32 v101, v101, v133
	v_add_f32_e32 v102, v102, v134
	v_add_f32_e32 v103, v103, v135
	s_waitcnt vmcnt(5)
	v_add_f32_e32 v104, v104, v136
	v_add_f32_e32 v105, v105, v137
	v_add_f32_e32 v106, v106, v138
	v_add_f32_e32 v107, v107, v139
	s_waitcnt vmcnt(4)
	v_add_f32_e32 v108, v108, v140
	v_add_f32_e32 v109, v109, v141
	v_add_f32_e32 v110, v110, v142
	v_add_f32_e32 v111, v111, v143
	s_waitcnt vmcnt(3)
	v_add_f32_e32 v112, v112, v144
	v_add_f32_e32 v113, v113, v145
	v_add_f32_e32 v114, v114, v146
	v_add_f32_e32 v115, v115, v147
	s_waitcnt vmcnt(2)
	v_add_f32_e32 v116, v116, v148
	v_add_f32_e32 v117, v117, v149
	v_add_f32_e32 v118, v118, v150
	v_add_f32_e32 v119, v119, v151
	s_waitcnt vmcnt(1)
	v_add_f32_e32 v120, v120, v152
	v_add_f32_e32 v121, v121, v153
	v_add_f32_e32 v122, v122, v154
	v_add_f32_e32 v123, v123, v155
	s_waitcnt vmcnt(0)
	v_add_f32_e32 v124, v124, v156
	v_add_f32_e32 v125, v125, v157
	v_add_f32_e32 v126, v126, v158
	v_add_f32_e32 v127, v127, v159
	s_add_u32 s92, s92, 0xc0000
	s_addc_u32 s93, s93, 0

.LBB0_1100:
	s_waitcnt lgkmcnt(0)
	v_mul_hi_i32 v1, v0, s52
	v_min_i32_e32 v2, 0x500dff, v0
	v_min_i32_e32 v3, 0x500bff, v0
	v_min_i32_e32 v4, 0x5009ff, v0
	v_add_u32_e32 v1, v1, v0
	v_add_u32_e32 v7, 0x200, v2
	v_add_u32_e32 v9, 0x400, v3
	v_add_u32_e32 v11, 0x600, v4
	v_lshrrev_b32_e32 v2, 31, v1
	v_ashrrev_i32_e32 v1, 17, v1
	v_mul_hi_i32 v3, v7, s52
	v_mul_hi_i32 v4, v9, s52
	v_mul_hi_i32 v5, v11, s52
	v_add_u32_e32 v2, v1, v2
	v_add_u32_e32 v1, v3, v7
	v_add_u32_e32 v6, v4, v9
	v_add_u32_e32 v5, v5, v11
	v_mad_i32_i24 v4, v2, s53, v0
	v_ashrrev_i32_e32 v3, 31, v2
	v_lshrrev_b32_e32 v8, 31, v1
	v_ashrrev_i32_e32 v1, 17, v1
	v_lshrrev_b32_e32 v10, 31, v6
	v_ashrrev_i32_e32 v12, 17, v6
	v_lshrrev_b32_e32 v13, 31, v5
	v_ashrrev_i32_e32 v14, 17, v5
	v_lshlrev_b64 v[2:3], 18, v[2:3]
	v_ashrrev_i32_e32 v5, 31, v4
	v_add_u32_e32 v6, v1, v8
	v_add_u32_e32 v8, v12, v10
	v_add_u32_e32 v10, v14, v13
	v_lshl_add_u64 v[2:3], v[2:3], 0, v[4:5]
	v_mad_i32_i24 v4, v6, s53, v7
	v_ashrrev_i32_e32 v7, 31, v6
	v_mad_i32_i24 v12, v8, s53, v9
	v_ashrrev_i32_e32 v9, 31, v8
	v_mad_i32_i24 v14, v10, s53, v11
	v_ashrrev_i32_e32 v11, 31, v10
	v_lshlrev_b64 v[164:165], 4, v[2:3]
	v_lshlrev_b64 v[2:3], 18, v[6:7]
	v_ashrrev_i32_e32 v5, 31, v4
	v_lshlrev_b64 v[6:7], 18, v[8:9]
	v_ashrrev_i32_e32 v13, 31, v12
	v_lshlrev_b64 v[8:9], 18, v[10:11]
	v_ashrrev_i32_e32 v15, 31, v14
	v_lshl_add_u64 v[10:11], s[82:83], 0, v[164:165]
	v_lshl_add_u64 v[2:3], v[2:3], 0, v[4:5]
	v_lshl_add_u64 v[4:5], v[6:7], 0, v[12:13]
	v_lshl_add_u64 v[6:7], v[8:9], 0, v[14:15]
	v_add_co_u32_e32 v8, vcc, s41, v10
	v_lshl_add_u64 v[144:145], s[84:85], 0, v[164:165]
	s_nop 0
	v_addc_co_u32_e32 v9, vcc, 0, v11, vcc
	v_lshlrev_b64 v[14:15], 4, v[2:3]
	v_lshlrev_b64 v[168:169], 4, v[6:7]
	v_add_co_u32_e32 v6, vcc, s41, v144
	v_lshl_add_u64 v[10:11], s[82:83], 0, v[14:15]
	s_nop 0
	v_addc_co_u32_e32 v7, vcc, 0, v145, vcc
	v_add_co_u32_e32 v10, vcc, s41, v10
	v_lshl_add_u64 v[12:13], s[84:85], 0, v[14:15]
	s_nop 0
	v_addc_co_u32_e32 v11, vcc, 0, v11, vcc
	v_lshlrev_b64 v[166:167], 4, v[4:5]
	v_add_co_u32_e32 v144, vcc, s41, v12
	v_lshl_add_u64 v[146:147], s[82:83], 0, v[166:167]
	s_nop 0
	v_addc_co_u32_e32 v145, vcc, 0, v13, vcc
	v_add_co_u32_e32 v154, vcc, s41, v146
	v_lshl_add_u64 v[148:149], s[84:85], 0, v[166:167]
	s_nop 0
	v_addc_co_u32_e32 v155, vcc, 0, v147, vcc
	v_add_co_u32_e32 v156, vcc, s41, v148
	v_lshl_add_u64 v[150:151], s[82:83], 0, v[168:169]
	s_nop 0
	v_addc_co_u32_e32 v157, vcc, 0, v149, vcc
	v_add_co_u32_e32 v158, vcc, s41, v150
	v_lshl_add_u64 v[152:153], s[84:85], 0, v[168:169]
	s_nop 0
	v_addc_co_u32_e32 v159, vcc, 0, v151, vcc
	v_add_co_u32_e32 v160, vcc, s41, v152
	global_load_dwordx4 v[2:5], v[8:9], off nt
	s_nop 0
	v_addc_co_u32_e32 v161, vcc, 0, v153, vcc
	global_load_dwordx4 v[6:9], v[6:7], off nt
	s_nop 0
	global_load_dwordx4 v[10:13], v[10:11], off nt
	s_nop 0
	global_load_dwordx4 v[144:147], v[144:145], off nt
	s_nop 0
	global_load_dwordx4 v[148:151], v[154:155], off nt
	s_nop 0
	global_load_dwordx4 v[152:155], v[156:157], off nt
	s_nop 0
	global_load_dwordx4 v[156:159], v[158:159], off nt
	s_nop 0
	global_load_dwordx4 v[160:163], v[160:161], off nt
	v_add_u32_e32 v0, s48, v0
	v_cmp_lt_i32_e32 vcc, s54, v0
	s_or_b64 s[26:27], vcc, s[26:27]
	v_lshl_add_u64 v[170:171], s[70:71], 0, v[164:165]
	v_lshl_add_u64 v[164:165], s[66:67], 0, v[164:165]
	v_lshl_add_u64 v[172:173], s[70:71], 0, v[14:15]
	v_lshl_add_u64 v[14:15], s[66:67], 0, v[14:15]
	v_lshl_add_u64 v[174:175], s[70:71], 0, v[166:167]
	v_lshl_add_u64 v[166:167], s[66:67], 0, v[166:167]
	v_lshl_add_u64 v[176:177], s[70:71], 0, v[168:169]
	v_lshl_add_u64 v[168:169], s[66:67], 0, v[168:169]
	s_waitcnt vmcnt(7)
	global_store_dwordx4 v[170:171], v[2:5], off nt
	s_waitcnt vmcnt(7)
	global_store_dwordx4 v[164:165], v[6:9], off nt
	s_waitcnt vmcnt(7)
	global_store_dwordx4 v[172:173], v[10:13], off nt
	s_waitcnt vmcnt(7)
	global_store_dwordx4 v[14:15], v[144:147], off nt
	s_waitcnt vmcnt(7)
	global_store_dwordx4 v[174:175], v[148:151], off nt
	s_waitcnt vmcnt(7)
	global_store_dwordx4 v[166:167], v[152:155], off nt
	s_waitcnt vmcnt(7)
	global_store_dwordx4 v[176:177], v[156:159], off nt
	s_waitcnt vmcnt(7)
	global_store_dwordx4 v[168:169], v[160:163], off nt
	s_andn2_b64 exec, exec, s[26:27]
	s_cbranch_execnz .LBB0_1100
